# v86 + mout readout: o-gate loads of each row block hoisted out of the store-load-wait chain
# speedup vs baseline: 1.0030x; 1.0030x over previous
.LBB1_99:
	v_mul_f32_e32 v116, v33, v35
	v_cvt_pk_bf16_f32 v32, v32, v36
	v_cvt_pk_bf16_f32 v33, v41, v38
	ds_write_b64 v43, v[32:33] offset:4576
	v_add_u32_e32 v56, v158, v42
	v_mul_f32_e32 v110, v45, v47
	v_mul_f32_e32 v114, v44, v46
	v_mul_f32_e32 v112, v34, v37
	s_waitcnt lgkmcnt(0)
	s_barrier
	ds_read_b128 v[32:35], v56
	ds_read_b128 v[36:39], v56 offset:64
	ds_read_b128 v[40:43], v56 offset:128
	ds_read_b128 v[88:91], v56 offset:192
	ds_read_b128 v[44:47], v56 offset:4352
	ds_read_b128 v[48:51], v56 offset:4416
	ds_read_b128 v[52:55], v56 offset:4480
	ds_read_b128 v[92:95], v56 offset:4544
	ds_read_b128 v[56:59], v157 offset:34816
	ds_read_b128 v[60:63], v157 offset:39168
	ds_read_b128 v[64:67], v157 offset:43520
	ds_read_b128 v[68:71], v157 offset:47872
	ds_read_b128 v[72:75], v157 offset:52224
	ds_read_b128 v[76:79], v157 offset:56576
	ds_read_b128 v[80:83], v157 offset:60928
	ds_read_b128 v[84:87], v157 offset:65280
	s_setprio 1
	s_waitcnt lgkmcnt(7)
	v_mfma_f32_16x16x32_bf16 v[96:99], v[56:59], v[32:35], 0
	v_mfma_f32_16x16x32_bf16 v[56:59], v[56:59], v[44:47], 0
	s_waitcnt lgkmcnt(6)
	v_mfma_f32_16x16x32_bf16 v[100:103], v[60:63], v[32:35], 0
	v_mfma_f32_16x16x32_bf16 v[60:63], v[60:63], v[44:47], 0
	s_waitcnt lgkmcnt(5)
	v_mfma_f32_16x16x32_bf16 v[118:121], v[64:67], v[32:35], 0
	v_mfma_f32_16x16x32_bf16 v[64:67], v[64:67], v[44:47], 0
	s_waitcnt lgkmcnt(4)
	v_mfma_f32_16x16x32_bf16 v[122:125], v[68:71], v[32:35], 0
	v_mfma_f32_16x16x32_bf16 v[68:71], v[68:71], v[44:47], 0
	s_waitcnt lgkmcnt(3)
	v_mfma_f32_16x16x32_bf16 v[130:133], v[72:75], v[32:35], 0
	v_mfma_f32_16x16x32_bf16 v[72:75], v[72:75], v[44:47], 0
	s_waitcnt lgkmcnt(2)
	v_mfma_f32_16x16x32_bf16 v[134:137], v[76:79], v[32:35], 0
	v_mfma_f32_16x16x32_bf16 v[76:79], v[76:79], v[44:47], 0
	s_waitcnt lgkmcnt(1)
	v_mfma_f32_16x16x32_bf16 v[138:141], v[80:83], v[32:35], 0
	v_mfma_f32_16x16x32_bf16 v[80:83], v[80:83], v[44:47], 0
	s_waitcnt lgkmcnt(0)
	v_mfma_f32_16x16x32_bf16 v[32:35], v[84:87], v[32:35], 0
	v_mfma_f32_16x16x32_bf16 v[44:47], v[84:87], v[44:47], 0
	s_setprio 0
	ds_read_b128 v[84:87], v157 offset:34880
	ds_read_b128 v[142:145], v157 offset:39232
	ds_read_b128 v[146:149], v157 offset:43584
	ds_read_b128 v[150:153], v157 offset:47936
	ds_read_b128 v[158:161], v157 offset:52288
	ds_read_b128 v[188:191], v157 offset:56640
	ds_read_b128 v[192:195], v157 offset:60992
	ds_read_b128 v[196:199], v157 offset:65344
	s_setprio 1
	s_waitcnt lgkmcnt(7)
	v_mfma_f32_16x16x32_bf16 v[96:99], v[84:87], v[36:39], v[96:99]
	v_mfma_f32_16x16x32_bf16 v[56:59], v[84:87], v[48:51], v[56:59]
	s_waitcnt lgkmcnt(6)
	v_mfma_f32_16x16x32_bf16 v[84:87], v[142:145], v[36:39], v[100:103]
	v_mfma_f32_16x16x32_bf16 v[60:63], v[142:145], v[48:51], v[60:63]
	s_waitcnt lgkmcnt(5)
	v_mfma_f32_16x16x32_bf16 v[100:103], v[146:149], v[36:39], v[118:121]
	v_mfma_f32_16x16x32_bf16 v[64:67], v[146:149], v[48:51], v[64:67]
	s_waitcnt lgkmcnt(4)
	v_mfma_f32_16x16x32_bf16 v[118:121], v[150:153], v[36:39], v[122:125]
	v_mfma_f32_16x16x32_bf16 v[68:71], v[150:153], v[48:51], v[68:71]
	s_waitcnt lgkmcnt(3)
	v_mfma_f32_16x16x32_bf16 v[122:125], v[158:161], v[36:39], v[130:133]
	v_mfma_f32_16x16x32_bf16 v[72:75], v[158:161], v[48:51], v[72:75]
	s_waitcnt lgkmcnt(2)
	v_mfma_f32_16x16x32_bf16 v[130:133], v[188:191], v[36:39], v[134:137]
	v_mfma_f32_16x16x32_bf16 v[76:79], v[188:191], v[48:51], v[76:79]
	s_waitcnt lgkmcnt(1)
	v_mfma_f32_16x16x32_bf16 v[134:137], v[192:195], v[36:39], v[138:141]
	v_mfma_f32_16x16x32_bf16 v[80:83], v[192:195], v[48:51], v[80:83]
	s_waitcnt lgkmcnt(0)
	v_mfma_f32_16x16x32_bf16 v[32:35], v[196:199], v[36:39], v[32:35]
	v_mfma_f32_16x16x32_bf16 v[36:39], v[196:199], v[48:51], v[44:47]
	s_setprio 0
	s_nop 1
	ds_read_b128 v[44:47], v157 offset:34944
	ds_read_b128 v[48:51], v157 offset:39296
	ds_read_b128 v[138:141], v157 offset:43648
	ds_read_b128 v[142:145], v157 offset:48000
	ds_read_b128 v[146:149], v157 offset:52352
	ds_read_b128 v[150:153], v157 offset:56704
	ds_read_b128 v[158:161], v157 offset:61056
	ds_read_b128 v[188:191], v157 offset:65408
	s_setprio 1
	s_waitcnt lgkmcnt(7)
	v_mfma_f32_16x16x32_bf16 v[96:99], v[44:47], v[40:43], v[96:99]
	v_mfma_f32_16x16x32_bf16 v[44:47], v[44:47], v[52:55], v[56:59]
	s_waitcnt lgkmcnt(6)
	v_mfma_f32_16x16x32_bf16 v[56:59], v[48:51], v[40:43], v[84:87]
	v_mfma_f32_16x16x32_bf16 v[48:51], v[48:51], v[52:55], v[60:63]
	s_waitcnt lgkmcnt(5)
	v_mfma_f32_16x16x32_bf16 v[60:63], v[138:141], v[40:43], v[100:103]
	v_mfma_f32_16x16x32_bf16 v[64:67], v[138:141], v[52:55], v[64:67]
	s_waitcnt lgkmcnt(4)
	v_mfma_f32_16x16x32_bf16 v[84:87], v[142:145], v[40:43], v[118:121]
	v_mfma_f32_16x16x32_bf16 v[68:71], v[142:145], v[52:55], v[68:71]
	s_waitcnt lgkmcnt(3)
	v_mfma_f32_16x16x32_bf16 v[100:103], v[146:149], v[40:43], v[122:125]
	v_mfma_f32_16x16x32_bf16 v[72:75], v[146:149], v[52:55], v[72:75]
	s_waitcnt lgkmcnt(2)
	v_mfma_f32_16x16x32_bf16 v[118:121], v[150:153], v[40:43], v[130:133]
	v_mfma_f32_16x16x32_bf16 v[76:79], v[150:153], v[52:55], v[76:79]
	s_waitcnt lgkmcnt(1)
	v_mfma_f32_16x16x32_bf16 v[122:125], v[158:161], v[40:43], v[134:137]
	v_mfma_f32_16x16x32_bf16 v[130:133], v[158:161], v[52:55], v[80:83]
	s_waitcnt lgkmcnt(0)
	v_mfma_f32_16x16x32_bf16 v[134:137], v[188:191], v[40:43], v[32:35]
	v_mfma_f32_16x16x32_bf16 v[138:141], v[188:191], v[52:55], v[36:39]
	s_setprio 0
	s_nop 1
	ds_read_b128 v[36:39], v157 offset:35008
	ds_read_b128 v[52:55], v157 offset:39360
	ds_read_b128 v[80:83], v157 offset:43712
	ds_read_b128 v[142:145], v157 offset:48064
	ds_read_b128 v[146:149], v157 offset:52416
	ds_read_b128 v[150:153], v157 offset:56768
	ds_read_b128 v[158:161], v157 offset:61120
	ds_read_b128 v[188:191], v157 offset:65472
	s_setprio 1
	s_waitcnt lgkmcnt(7)
	v_mfma_f32_16x16x32_bf16 v[32:35], v[36:39], v[88:91], v[96:99]
	v_mfma_f32_16x16x32_bf16 v[36:39], v[36:39], v[92:95], v[44:47]
	s_waitcnt lgkmcnt(6)
	v_mfma_f32_16x16x32_bf16 v[40:43], v[52:55], v[88:91], v[56:59]
	v_mfma_f32_16x16x32_bf16 v[44:47], v[52:55], v[92:95], v[48:51]
	s_waitcnt lgkmcnt(5)
	v_mfma_f32_16x16x32_bf16 v[48:51], v[80:83], v[88:91], v[60:63]
	v_mfma_f32_16x16x32_bf16 v[52:55], v[80:83], v[92:95], v[64:67]
	s_waitcnt lgkmcnt(4)
	v_mfma_f32_16x16x32_bf16 v[56:59], v[142:145], v[88:91], v[84:87]
	v_mfma_f32_16x16x32_bf16 v[60:63], v[142:145], v[92:95], v[68:71]
	s_waitcnt lgkmcnt(3)
	v_mfma_f32_16x16x32_bf16 v[64:67], v[146:149], v[88:91], v[100:103]
	v_mfma_f32_16x16x32_bf16 v[68:71], v[146:149], v[92:95], v[72:75]
	s_waitcnt lgkmcnt(2)
	v_mfma_f32_16x16x32_bf16 v[72:75], v[150:153], v[88:91], v[118:121]
	v_mfma_f32_16x16x32_bf16 v[76:79], v[150:153], v[92:95], v[76:79]
	s_waitcnt lgkmcnt(1)
	v_mfma_f32_16x16x32_bf16 v[80:83], v[158:161], v[88:91], v[122:125]
	v_mfma_f32_16x16x32_bf16 v[84:87], v[158:161], v[92:95], v[130:133]
	s_waitcnt lgkmcnt(0)
	v_mfma_f32_16x16x32_bf16 v[88:91], v[188:191], v[88:91], v[134:137]
	v_mfma_f32_16x16x32_bf16 v[92:95], v[188:191], v[92:95], v[138:141]
	s_setprio 0
	s_lshl_b64 s[4:5], s[70:71], 15
	s_add_u32 s4, s80, s4
	s_addc_u32 s5, s81, s5
	v_lshlrev_b64 v[96:97], 8, v[104:105]
	v_lshl_add_u64 v[98:99], s[4:5], 0, v[96:97]
	s_lshl_b64 s[4:5], s[68:69], 15
	s_add_u32 s4, s80, s4
	s_addc_u32 s5, s81, s5
	v_lshl_add_u64 v[100:101], v[98:99], 0, v[128:129]
	v_lshl_add_u64 v[96:97], s[4:5], 0, v[96:97]
	s_barrier
	v_lshl_add_u64 v[102:103], v[96:97], 0, v[128:129]
	global_load_dwordx4 v[204:207], v[100:101], off
	s_movk_i32 s5, 0x2000
	v_add_co_u32_e32 v104, vcc, s5, v100
	s_movk_i32 s2, 0x4000
	s_nop 0
	v_addc_co_u32_e32 v105, vcc, 0, v101, vcc
	s_movk_i32 s4, 0x6000
	s_movk_i32 s6, 0x7000
	v_mov_b64_e32 v[132:133], v[10:11]
	v_mov_b64_e32 v[130:131], v[8:9]
	v_mov_b64_e32 v[136:137], v[6:7]
	v_mov_b64_e32 v[134:135], v[4:5]
	v_mov_b64_e32 v[140:141], v[2:3]
	v_mov_b64_e32 v[138:139], v[0:1]
	global_load_dwordx4 v[208:211], v[104:105], off offset:-4096
	global_load_dwordx4 v[216:219], v[104:105], off
	v_add_co_u32_e32 v104, vcc, s2, v100
	v_addc_co_u32_e32 v105, vcc, 0, v101, vcc
	global_load_dwordx4 v[220:223], v[104:105], off offset:-4096
	global_load_dwordx4 v[224:227], v[104:105], off
	v_add_co_u32_e32 v104, vcc, s4, v100
	v_addc_co_u32_e32 v105, vcc, 0, v101, vcc
	global_load_dwordx4 v[228:231], v[104:105], off offset:-4096
	global_load_dwordx4 v[232:235], v[104:105], off
	v_add_co_u32_e32 v96, vcc, s6, v100
	s_nop 1
	v_addc_co_u32_e32 v97, vcc, 0, v101, vcc
	global_load_dwordx4 v[236:239], v[96:97], off
	s_waitcnt vmcnt(0)
	ds_write_b128 v107, v[204:207]
	ds_write_b128 v107, v[208:211] offset:4352
	ds_write_b128 v107, v[216:219] offset:8704
	ds_write_b128 v107, v[220:223] offset:13056
	ds_write_b128 v107, v[224:227] offset:17408
	ds_write_b128 v107, v[228:231] offset:21760
	ds_write_b128 v107, v[232:235] offset:26112
	ds_write_b128 v107, v[236:239] offset:30464
	v_add_co_u32_e32 v100, vcc, s5, v102
	global_load_dwordx4 v[204:207], v[102:103], off
	v_addc_co_u32_e32 v101, vcc, 0, v103, vcc
	global_load_dwordx4 v[208:211], v[100:101], off offset:-4096
	global_load_dwordx4 v[216:219], v[100:101], off
	v_add_co_u32_e32 v100, vcc, s2, v102
	v_addc_co_u32_e32 v101, vcc, 0, v103, vcc
	global_load_dwordx4 v[220:223], v[100:101], off offset:-4096
	global_load_dwordx4 v[224:227], v[100:101], off
	v_add_co_u32_e32 v100, vcc, s4, v102
	v_addc_co_u32_e32 v101, vcc, 0, v103, vcc
	global_load_dwordx4 v[228:231], v[100:101], off offset:-4096
	global_load_dwordx4 v[232:235], v[100:101], off
	v_add_co_u32_e32 v96, vcc, s6, v102
	s_nop 1
	v_addc_co_u32_e32 v97, vcc, 0, v103, vcc
	global_load_dwordx4 v[236:239], v[96:97], off
	s_waitcnt vmcnt(0)
	ds_write_b128 v107, v[204:207] offset:34816
	ds_write_b128 v107, v[208:211] offset:39168
	ds_write_b128 v107, v[216:219] offset:43520
	ds_write_b128 v107, v[220:223] offset:47872
	ds_write_b128 v107, v[224:227] offset:52224
	ds_write_b128 v107, v[228:231] offset:56576
	ds_write_b128 v107, v[232:235] offset:60928
	ds_write_b128 v107, v[236:239] offset:65280
	v_mov_b64_e32 v[98:99], v[30:31]
	v_mov_b64_e32 v[96:97], v[28:29]
	s_waitcnt lgkmcnt(0)
	s_barrier
	s_nop 0
	v_lshlrev_b32_e32 v100, 16, v96
	v_and_b32_e32 v101, 0xffff0000, v96
	v_pk_mul_f32 v[100:101], v[116:117], v[100:101] op_sel_hi:[0,1]
	v_cvt_pk_bf16_f32 v96, v100, v101
	v_lshlrev_b32_e32 v100, 16, v97
	v_and_b32_e32 v101, 0xffff0000, v97
	v_pk_mul_f32 v[100:101], v[116:117], v[100:101] op_sel_hi:[0,1]
	v_cvt_pk_bf16_f32 v97, v100, v101
	v_lshlrev_b32_e32 v100, 16, v98
	v_and_b32_e32 v101, 0xffff0000, v98
	v_pk_mul_f32 v[100:101], v[116:117], v[100:101] op_sel_hi:[0,1]
	v_cvt_pk_bf16_f32 v98, v100, v101
	v_lshlrev_b32_e32 v100, 16, v99
	v_and_b32_e32 v101, 0xffff0000, v99
	v_pk_mul_f32 v[100:101], v[116:117], v[100:101] op_sel_hi:[0,1]
	v_cvt_pk_bf16_f32 v99, v100, v101
	v_mov_b64_e32 v[102:103], v[26:27]
	v_mov_b64_e32 v[100:101], v[24:25]
	s_nop 0
	v_lshlrev_b32_e32 v104, 16, v100
	v_and_b32_e32 v105, 0xffff0000, v100
	v_pk_mul_f32 v[104:105], v[114:115], v[104:105] op_sel_hi:[0,1]
	v_cvt_pk_bf16_f32 v100, v104, v105
	v_lshlrev_b32_e32 v104, 16, v101
	v_and_b32_e32 v105, 0xffff0000, v101
	v_pk_mul_f32 v[104:105], v[114:115], v[104:105] op_sel_hi:[0,1]
	v_cvt_pk_bf16_f32 v101, v104, v105
	v_lshlrev_b32_e32 v104, 16, v102
	v_and_b32_e32 v105, 0xffff0000, v102
	v_pk_mul_f32 v[104:105], v[114:115], v[104:105] op_sel_hi:[0,1]
	v_cvt_pk_bf16_f32 v102, v104, v105
	v_lshlrev_b32_e32 v104, 16, v103
	v_and_b32_e32 v105, 0xffff0000, v103
	v_pk_mul_f32 v[104:105], v[114:115], v[104:105] op_sel_hi:[0,1]
	v_cvt_pk_bf16_f32 v103, v104, v105
	v_mov_b64_e32 v[106:107], v[22:23]
	v_mov_b64_e32 v[104:105], v[20:21]
	s_nop 0
	v_lshlrev_b32_e32 v118, 16, v104
	v_and_b32_e32 v119, 0xffff0000, v104
	v_pk_mul_f32 v[118:119], v[116:117], v[118:119] op_sel_hi:[0,1]
	v_cvt_pk_bf16_f32 v104, v118, v119
	v_lshlrev_b32_e32 v118, 16, v105
	v_and_b32_e32 v119, 0xffff0000, v105
	v_pk_mul_f32 v[118:119], v[116:117], v[118:119] op_sel_hi:[0,1]
	v_cvt_pk_bf16_f32 v105, v118, v119
	v_lshlrev_b32_e32 v118, 16, v106
	v_and_b32_e32 v119, 0xffff0000, v106
	v_pk_mul_f32 v[118:119], v[116:117], v[118:119] op_sel_hi:[0,1]
	v_cvt_pk_bf16_f32 v106, v118, v119
	v_lshlrev_b32_e32 v118, 16, v107
	v_and_b32_e32 v119, 0xffff0000, v107
	v_pk_mul_f32 v[118:119], v[116:117], v[118:119] op_sel_hi:[0,1]
	v_cvt_pk_bf16_f32 v107, v118, v119
	v_mov_b64_e32 v[120:121], v[18:19]
	v_mov_b64_e32 v[118:119], v[16:17]
	s_nop 0
	v_lshlrev_b32_e32 v122, 16, v118
	v_and_b32_e32 v123, 0xffff0000, v118
	v_pk_mul_f32 v[122:123], v[114:115], v[122:123] op_sel_hi:[0,1]
	v_cvt_pk_bf16_f32 v118, v122, v123
	v_lshlrev_b32_e32 v122, 16, v119
	v_and_b32_e32 v123, 0xffff0000, v119
	v_pk_mul_f32 v[122:123], v[114:115], v[122:123] op_sel_hi:[0,1]
	v_cvt_pk_bf16_f32 v119, v122, v123
	v_lshlrev_b32_e32 v122, 16, v120
	v_and_b32_e32 v123, 0xffff0000, v120
	v_pk_mul_f32 v[122:123], v[114:115], v[122:123] op_sel_hi:[0,1]
	v_cvt_pk_bf16_f32 v120, v122, v123
	v_lshlrev_b32_e32 v122, 16, v121
	v_and_b32_e32 v123, 0xffff0000, v121
	v_pk_mul_f32 v[122:123], v[114:115], v[122:123] op_sel_hi:[0,1]
	v_cvt_pk_bf16_f32 v121, v122, v123
	v_mov_b64_e32 v[124:125], v[14:15]
	v_mov_b64_e32 v[122:123], v[12:13]
	s_nop 0
	v_lshlrev_b32_e32 v126, 16, v122
	v_and_b32_e32 v127, 0xffff0000, v122
	v_pk_mul_f32 v[126:127], v[116:117], v[126:127] op_sel_hi:[0,1]
	v_cvt_pk_bf16_f32 v122, v126, v127
	v_lshlrev_b32_e32 v126, 16, v123
	v_and_b32_e32 v127, 0xffff0000, v123
	v_pk_mul_f32 v[126:127], v[116:117], v[126:127] op_sel_hi:[0,1]
	v_cvt_pk_bf16_f32 v123, v126, v127
	v_lshlrev_b32_e32 v126, 16, v124
	v_and_b32_e32 v127, 0xffff0000, v124
	v_pk_mul_f32 v[126:127], v[116:117], v[126:127] op_sel_hi:[0,1]
	v_cvt_pk_bf16_f32 v124, v126, v127
	v_lshlrev_b32_e32 v126, 16, v125
	v_and_b32_e32 v127, 0xffff0000, v125
	v_pk_mul_f32 v[126:127], v[116:117], v[126:127] op_sel_hi:[0,1]
	v_cvt_pk_bf16_f32 v125, v126, v127
	v_lshlrev_b32_e32 v126, 16, v130
	v_and_b32_e32 v127, 0xffff0000, v130
	v_pk_mul_f32 v[126:127], v[114:115], v[126:127] op_sel_hi:[0,1]
	v_cvt_pk_bf16_f32 v130, v126, v127
	v_lshlrev_b32_e32 v126, 16, v131
	v_and_b32_e32 v127, 0xffff0000, v131
	v_pk_mul_f32 v[126:127], v[114:115], v[126:127] op_sel_hi:[0,1]
	v_cvt_pk_bf16_f32 v131, v126, v127
	v_lshlrev_b32_e32 v126, 16, v132
	v_and_b32_e32 v127, 0xffff0000, v132
	v_pk_mul_f32 v[126:127], v[114:115], v[126:127] op_sel_hi:[0,1]
	v_cvt_pk_bf16_f32 v132, v126, v127
	v_lshlrev_b32_e32 v126, 16, v133
	v_and_b32_e32 v127, 0xffff0000, v133
	v_pk_mul_f32 v[126:127], v[114:115], v[126:127] op_sel_hi:[0,1]
	v_cvt_pk_bf16_f32 v133, v126, v127
	v_lshlrev_b32_e32 v126, 16, v134
	v_and_b32_e32 v127, 0xffff0000, v134
	v_pk_mul_f32 v[126:127], v[116:117], v[126:127] op_sel_hi:[0,1]
	v_cvt_pk_bf16_f32 v134, v126, v127
	v_lshlrev_b32_e32 v126, 16, v135
	v_and_b32_e32 v127, 0xffff0000, v135
	v_pk_mul_f32 v[126:127], v[116:117], v[126:127] op_sel_hi:[0,1]
	v_cvt_pk_bf16_f32 v135, v126, v127
	v_lshlrev_b32_e32 v126, 16, v136
	v_and_b32_e32 v127, 0xffff0000, v136
	v_pk_mul_f32 v[126:127], v[116:117], v[126:127] op_sel_hi:[0,1]
	v_cvt_pk_bf16_f32 v136, v126, v127
	v_lshlrev_b32_e32 v126, 16, v137
	v_and_b32_e32 v127, 0xffff0000, v137
	v_pk_mul_f32 v[116:117], v[116:117], v[126:127] op_sel_hi:[0,1]
	v_cvt_pk_bf16_f32 v137, v116, v117
	v_lshlrev_b32_e32 v116, 16, v138
	v_and_b32_e32 v117, 0xffff0000, v138
	v_pk_mul_f32 v[116:117], v[114:115], v[116:117] op_sel_hi:[0,1]
	v_cvt_pk_bf16_f32 v138, v116, v117
	v_lshlrev_b32_e32 v116, 16, v139
	v_and_b32_e32 v117, 0xffff0000, v139
	v_pk_mul_f32 v[116:117], v[114:115], v[116:117] op_sel_hi:[0,1]
	v_cvt_pk_bf16_f32 v139, v116, v117
	v_lshlrev_b32_e32 v116, 16, v140
	v_and_b32_e32 v117, 0xffff0000, v140
	v_pk_mul_f32 v[116:117], v[114:115], v[116:117] op_sel_hi:[0,1]
	v_cvt_pk_bf16_f32 v140, v116, v117
	v_lshlrev_b32_e32 v116, 16, v141
	v_and_b32_e32 v117, 0xffff0000, v141
	v_pk_mul_f32 v[114:115], v[114:115], v[116:117] op_sel_hi:[0,1]
	v_cvt_pk_bf16_f32 v141, v114, v115
	ds_read_b128 v[114:117], v157
	ds_read_b128 v[142:145], v157 offset:4352
	ds_read_b128 v[146:149], v157 offset:8704
	ds_read_b128 v[150:153], v157 offset:13056
	ds_read_b128 v[158:161], v157 offset:17408
	ds_read_b128 v[188:191], v157 offset:21760
	ds_read_b128 v[192:195], v157 offset:26112
	ds_read_b128 v[196:199], v157 offset:30464
	s_setprio 1
	s_waitcnt lgkmcnt(7)
	v_mfma_f32_16x16x32_bf16 v[32:35], v[114:117], v[96:99], v[32:35]
	v_mfma_f32_16x16x32_bf16 v[36:39], v[114:117], v[100:103], v[36:39]
	s_waitcnt lgkmcnt(6)
	v_mfma_f32_16x16x32_bf16 v[40:43], v[142:145], v[96:99], v[40:43]
	v_mfma_f32_16x16x32_bf16 v[44:47], v[142:145], v[100:103], v[44:47]
	s_waitcnt lgkmcnt(5)
	v_mfma_f32_16x16x32_bf16 v[48:51], v[146:149], v[96:99], v[48:51]
	v_mfma_f32_16x16x32_bf16 v[52:55], v[146:149], v[100:103], v[52:55]
	s_waitcnt lgkmcnt(4)
	v_mfma_f32_16x16x32_bf16 v[56:59], v[150:153], v[96:99], v[56:59]
	v_mfma_f32_16x16x32_bf16 v[60:63], v[150:153], v[100:103], v[60:63]
	s_waitcnt lgkmcnt(3)
	v_mfma_f32_16x16x32_bf16 v[64:67], v[158:161], v[96:99], v[64:67]
	v_mfma_f32_16x16x32_bf16 v[68:71], v[158:161], v[100:103], v[68:71]
	s_waitcnt lgkmcnt(2)
	v_mfma_f32_16x16x32_bf16 v[72:75], v[188:191], v[96:99], v[72:75]
	v_mfma_f32_16x16x32_bf16 v[76:79], v[188:191], v[100:103], v[76:79]
	s_waitcnt lgkmcnt(1)
	v_mfma_f32_16x16x32_bf16 v[80:83], v[192:195], v[96:99], v[80:83]
	v_mfma_f32_16x16x32_bf16 v[84:87], v[192:195], v[100:103], v[84:87]
	s_waitcnt lgkmcnt(0)
	v_mfma_f32_16x16x32_bf16 v[88:91], v[196:199], v[96:99], v[88:91]
	v_mfma_f32_16x16x32_bf16 v[92:95], v[196:199], v[100:103], v[92:95]
	s_setprio 0
	ds_read_b128 v[96:99], v157 offset:64
	ds_read_b128 v[100:103], v157 offset:4416
	ds_read_b128 v[114:117], v157 offset:8768
	ds_read_b128 v[142:145], v157 offset:13120
	ds_read_b128 v[146:149], v157 offset:17472
	ds_read_b128 v[150:153], v157 offset:21824
	ds_read_b128 v[158:161], v157 offset:26176
	ds_read_b128 v[188:191], v157 offset:30528
	s_setprio 1
	s_waitcnt lgkmcnt(7)
	v_mfma_f32_16x16x32_bf16 v[32:35], v[96:99], v[104:107], v[32:35]
	v_mfma_f32_16x16x32_bf16 v[36:39], v[96:99], v[118:121], v[36:39]
	s_waitcnt lgkmcnt(6)
	v_mfma_f32_16x16x32_bf16 v[40:43], v[100:103], v[104:107], v[40:43]
	v_mfma_f32_16x16x32_bf16 v[44:47], v[100:103], v[118:121], v[44:47]
	s_waitcnt lgkmcnt(5)
	v_mfma_f32_16x16x32_bf16 v[48:51], v[114:117], v[104:107], v[48:51]
	v_mfma_f32_16x16x32_bf16 v[52:55], v[114:117], v[118:121], v[52:55]
	s_waitcnt lgkmcnt(4)
	v_mfma_f32_16x16x32_bf16 v[56:59], v[142:145], v[104:107], v[56:59]
	v_mfma_f32_16x16x32_bf16 v[60:63], v[142:145], v[118:121], v[60:63]
	s_waitcnt lgkmcnt(3)
	v_mfma_f32_16x16x32_bf16 v[64:67], v[146:149], v[104:107], v[64:67]
	v_mfma_f32_16x16x32_bf16 v[68:71], v[146:149], v[118:121], v[68:71]
	s_waitcnt lgkmcnt(2)
	v_mfma_f32_16x16x32_bf16 v[72:75], v[150:153], v[104:107], v[72:75]
	v_mfma_f32_16x16x32_bf16 v[76:79], v[150:153], v[118:121], v[76:79]
	s_waitcnt lgkmcnt(1)
	v_mfma_f32_16x16x32_bf16 v[80:83], v[158:161], v[104:107], v[80:83]
	v_mfma_f32_16x16x32_bf16 v[84:87], v[158:161], v[118:121], v[84:87]
	s_waitcnt lgkmcnt(0)
	v_mfma_f32_16x16x32_bf16 v[88:91], v[188:191], v[104:107], v[88:91]
	v_mfma_f32_16x16x32_bf16 v[92:95], v[188:191], v[118:121], v[92:95]
	s_setprio 0
	ds_read_b128 v[96:99], v157 offset:128
	ds_read_b128 v[100:103], v157 offset:4480
	ds_read_b128 v[104:107], v157 offset:8832
	ds_read_b128 v[114:117], v157 offset:13184
	ds_read_b128 v[118:121], v157 offset:17536
	ds_read_b128 v[142:145], v157 offset:21888
	ds_read_b128 v[146:149], v157 offset:26240
	ds_read_b128 v[150:153], v157 offset:30592
	s_setprio 1
	s_waitcnt lgkmcnt(7)
	v_mfma_f32_16x16x32_bf16 v[32:35], v[96:99], v[122:125], v[32:35]
	v_mfma_f32_16x16x32_bf16 v[36:39], v[96:99], v[130:133], v[36:39]
	s_waitcnt lgkmcnt(6)
	v_mfma_f32_16x16x32_bf16 v[40:43], v[100:103], v[122:125], v[40:43]
	v_mfma_f32_16x16x32_bf16 v[44:47], v[100:103], v[130:133], v[44:47]
	s_waitcnt lgkmcnt(5)
	v_mfma_f32_16x16x32_bf16 v[48:51], v[104:107], v[122:125], v[48:51]
	v_mfma_f32_16x16x32_bf16 v[52:55], v[104:107], v[130:133], v[52:55]
	s_waitcnt lgkmcnt(4)
	v_mfma_f32_16x16x32_bf16 v[56:59], v[114:117], v[122:125], v[56:59]
	v_mfma_f32_16x16x32_bf16 v[60:63], v[114:117], v[130:133], v[60:63]
	s_waitcnt lgkmcnt(3)
	v_mfma_f32_16x16x32_bf16 v[64:67], v[118:121], v[122:125], v[64:67]
	v_mfma_f32_16x16x32_bf16 v[68:71], v[118:121], v[130:133], v[68:71]
	s_waitcnt lgkmcnt(2)
	v_mfma_f32_16x16x32_bf16 v[72:75], v[142:145], v[122:125], v[72:75]
	v_mfma_f32_16x16x32_bf16 v[76:79], v[142:145], v[130:133], v[76:79]
	s_waitcnt lgkmcnt(1)
	v_mfma_f32_16x16x32_bf16 v[80:83], v[146:149], v[122:125], v[80:83]
	v_mfma_f32_16x16x32_bf16 v[84:87], v[146:149], v[130:133], v[84:87]
	s_waitcnt lgkmcnt(0)
	v_mfma_f32_16x16x32_bf16 v[88:91], v[150:153], v[122:125], v[88:91]
	v_mfma_f32_16x16x32_bf16 v[92:95], v[150:153], v[130:133], v[92:95]
	s_setprio 0
	ds_read_b128 v[96:99], v157 offset:192
	ds_read_b128 v[100:103], v157 offset:4544
	ds_read_b128 v[104:107], v157 offset:8896
	ds_read_b128 v[114:117], v157 offset:13248
	ds_read_b128 v[118:121], v157 offset:17600
	ds_read_b128 v[122:125], v157 offset:21952
	ds_read_b128 v[130:133], v157 offset:26304
	ds_read_b128 v[142:145], v157 offset:30656
	s_setprio 1
	s_waitcnt lgkmcnt(7)
	v_mfma_f32_16x16x32_bf16 v[32:35], v[96:99], v[134:137], v[32:35]
	v_mfma_f32_16x16x32_bf16 v[36:39], v[96:99], v[138:141], v[36:39]
	s_waitcnt lgkmcnt(6)
	v_mfma_f32_16x16x32_bf16 v[40:43], v[100:103], v[134:137], v[40:43]
	v_mfma_f32_16x16x32_bf16 v[44:47], v[100:103], v[138:141], v[44:47]
	s_waitcnt lgkmcnt(5)
	v_mfma_f32_16x16x32_bf16 v[48:51], v[104:107], v[134:137], v[48:51]
	v_mfma_f32_16x16x32_bf16 v[52:55], v[104:107], v[138:141], v[52:55]
	s_waitcnt lgkmcnt(4)
	v_mfma_f32_16x16x32_bf16 v[56:59], v[114:117], v[134:137], v[56:59]
	v_mfma_f32_16x16x32_bf16 v[60:63], v[114:117], v[138:141], v[60:63]
	s_waitcnt lgkmcnt(3)
	v_mfma_f32_16x16x32_bf16 v[64:67], v[118:121], v[134:137], v[64:67]
	v_mfma_f32_16x16x32_bf16 v[68:71], v[118:121], v[138:141], v[68:71]
	s_waitcnt lgkmcnt(2)
	v_mfma_f32_16x16x32_bf16 v[72:75], v[122:125], v[134:137], v[72:75]
	v_mfma_f32_16x16x32_bf16 v[76:79], v[122:125], v[138:141], v[76:79]
	s_waitcnt lgkmcnt(1)
	v_mfma_f32_16x16x32_bf16 v[80:83], v[130:133], v[134:137], v[80:83]
	v_mfma_f32_16x16x32_bf16 v[84:87], v[130:133], v[138:141], v[84:87]
	s_waitcnt lgkmcnt(0)
	v_mfma_f32_16x16x32_bf16 v[88:91], v[142:145], v[134:137], v[88:91]
	v_mfma_f32_16x16x32_bf16 v[92:95], v[142:145], v[138:141], v[92:95]
	s_setprio 0
	s_nop 0
	v_lshlrev_b32_e32 v96, 16, v28
	v_and_b32_e32 v97, 0xffff0000, v28
	v_pk_mul_f32 v[96:97], v[112:113], v[96:97] op_sel_hi:[0,1]
	v_cvt_pk_bf16_f32 v28, v96, v97
	v_lshlrev_b32_e32 v96, 16, v29
	v_and_b32_e32 v97, 0xffff0000, v29
	v_pk_mul_f32 v[96:97], v[112:113], v[96:97] op_sel_hi:[0,1]
	v_cvt_pk_bf16_f32 v29, v96, v97
	v_lshlrev_b32_e32 v96, 16, v30
	v_and_b32_e32 v97, 0xffff0000, v30
	v_pk_mul_f32 v[96:97], v[112:113], v[96:97] op_sel_hi:[0,1]
	v_cvt_pk_bf16_f32 v30, v96, v97
	v_lshlrev_b32_e32 v96, 16, v31
	v_and_b32_e32 v97, 0xffff0000, v31
	v_pk_mul_f32 v[96:97], v[112:113], v[96:97] op_sel_hi:[0,1]
	v_cvt_pk_bf16_f32 v31, v96, v97
	v_lshlrev_b32_e32 v96, 16, v24
	v_and_b32_e32 v97, 0xffff0000, v24
	v_pk_mul_f32 v[96:97], v[110:111], v[96:97] op_sel_hi:[0,1]
	v_cvt_pk_bf16_f32 v24, v96, v97
	v_lshlrev_b32_e32 v96, 16, v25
	v_and_b32_e32 v97, 0xffff0000, v25
	v_pk_mul_f32 v[96:97], v[110:111], v[96:97] op_sel_hi:[0,1]
	v_cvt_pk_bf16_f32 v25, v96, v97
	v_lshlrev_b32_e32 v96, 16, v26
	v_and_b32_e32 v97, 0xffff0000, v26
	v_pk_mul_f32 v[96:97], v[110:111], v[96:97] op_sel_hi:[0,1]
	v_cvt_pk_bf16_f32 v26, v96, v97
	v_lshlrev_b32_e32 v96, 16, v27
	v_and_b32_e32 v97, 0xffff0000, v27
	v_pk_mul_f32 v[96:97], v[110:111], v[96:97] op_sel_hi:[0,1]
	v_cvt_pk_bf16_f32 v27, v96, v97
	v_lshlrev_b32_e32 v96, 16, v20
	v_and_b32_e32 v97, 0xffff0000, v20
	v_pk_mul_f32 v[96:97], v[112:113], v[96:97] op_sel_hi:[0,1]
	v_cvt_pk_bf16_f32 v20, v96, v97
	v_lshlrev_b32_e32 v96, 16, v21
	v_and_b32_e32 v97, 0xffff0000, v21
	v_pk_mul_f32 v[96:97], v[112:113], v[96:97] op_sel_hi:[0,1]
	v_cvt_pk_bf16_f32 v21, v96, v97
	v_lshlrev_b32_e32 v96, 16, v22
	v_and_b32_e32 v97, 0xffff0000, v22
	v_pk_mul_f32 v[96:97], v[112:113], v[96:97] op_sel_hi:[0,1]
	v_cvt_pk_bf16_f32 v22, v96, v97
	v_lshlrev_b32_e32 v96, 16, v23
	v_and_b32_e32 v97, 0xffff0000, v23
	v_pk_mul_f32 v[96:97], v[112:113], v[96:97] op_sel_hi:[0,1]
	v_cvt_pk_bf16_f32 v23, v96, v97
	v_lshlrev_b32_e32 v96, 16, v16
	v_and_b32_e32 v97, 0xffff0000, v16
	v_pk_mul_f32 v[96:97], v[110:111], v[96:97] op_sel_hi:[0,1]
	v_cvt_pk_bf16_f32 v16, v96, v97
	v_lshlrev_b32_e32 v96, 16, v17
	v_and_b32_e32 v97, 0xffff0000, v17
	v_pk_mul_f32 v[96:97], v[110:111], v[96:97] op_sel_hi:[0,1]
	v_cvt_pk_bf16_f32 v17, v96, v97
	v_lshlrev_b32_e32 v96, 16, v18
	v_and_b32_e32 v97, 0xffff0000, v18
	v_pk_mul_f32 v[96:97], v[110:111], v[96:97] op_sel_hi:[0,1]
	v_cvt_pk_bf16_f32 v18, v96, v97
	v_lshlrev_b32_e32 v96, 16, v19
	v_and_b32_e32 v97, 0xffff0000, v19
	v_pk_mul_f32 v[96:97], v[110:111], v[96:97] op_sel_hi:[0,1]
	v_cvt_pk_bf16_f32 v19, v96, v97
	v_lshlrev_b32_e32 v96, 16, v12
	v_and_b32_e32 v97, 0xffff0000, v12
	v_pk_mul_f32 v[96:97], v[112:113], v[96:97] op_sel_hi:[0,1]
	v_cvt_pk_bf16_f32 v12, v96, v97
	v_lshlrev_b32_e32 v96, 16, v13
	v_and_b32_e32 v97, 0xffff0000, v13
	v_pk_mul_f32 v[96:97], v[112:113], v[96:97] op_sel_hi:[0,1]
	v_cvt_pk_bf16_f32 v13, v96, v97
	v_lshlrev_b32_e32 v96, 16, v14
	v_and_b32_e32 v97, 0xffff0000, v14
	v_pk_mul_f32 v[96:97], v[112:113], v[96:97] op_sel_hi:[0,1]
	v_cvt_pk_bf16_f32 v14, v96, v97
	v_lshlrev_b32_e32 v96, 16, v15
	v_and_b32_e32 v97, 0xffff0000, v15
	v_pk_mul_f32 v[96:97], v[112:113], v[96:97] op_sel_hi:[0,1]
	v_cvt_pk_bf16_f32 v15, v96, v97
	v_lshlrev_b32_e32 v96, 16, v8
	v_and_b32_e32 v97, 0xffff0000, v8
	v_pk_mul_f32 v[96:97], v[110:111], v[96:97] op_sel_hi:[0,1]
	v_cvt_pk_bf16_f32 v8, v96, v97
	v_lshlrev_b32_e32 v96, 16, v9
	v_and_b32_e32 v97, 0xffff0000, v9
	v_pk_mul_f32 v[96:97], v[110:111], v[96:97] op_sel_hi:[0,1]
	v_cvt_pk_bf16_f32 v9, v96, v97
	v_lshlrev_b32_e32 v96, 16, v10
	v_and_b32_e32 v97, 0xffff0000, v10
	v_pk_mul_f32 v[96:97], v[110:111], v[96:97] op_sel_hi:[0,1]
	v_cvt_pk_bf16_f32 v10, v96, v97
	v_lshlrev_b32_e32 v96, 16, v11
	v_and_b32_e32 v97, 0xffff0000, v11
	v_pk_mul_f32 v[96:97], v[110:111], v[96:97] op_sel_hi:[0,1]
	v_cvt_pk_bf16_f32 v11, v96, v97
	v_lshlrev_b32_e32 v96, 16, v4
	v_and_b32_e32 v97, 0xffff0000, v4
	v_lshlrev_b32_e32 v4, 16, v5
	v_and_b32_e32 v5, 0xffff0000, v5
	v_pk_mul_f32 v[96:97], v[112:113], v[96:97] op_sel_hi:[0,1]
	v_pk_mul_f32 v[4:5], v[112:113], v[4:5] op_sel_hi:[0,1]
	v_cvt_pk_bf16_f32 v96, v96, v97
	v_cvt_pk_bf16_f32 v97, v4, v5
	v_lshlrev_b32_e32 v4, 16, v6
	v_and_b32_e32 v5, 0xffff0000, v6
	v_pk_mul_f32 v[4:5], v[112:113], v[4:5] op_sel_hi:[0,1]
	v_cvt_pk_bf16_f32 v98, v4, v5
	v_lshlrev_b32_e32 v4, 16, v7
	v_and_b32_e32 v5, 0xffff0000, v7
	v_pk_mul_f32 v[4:5], v[112:113], v[4:5] op_sel_hi:[0,1]
	v_cvt_pk_bf16_f32 v99, v4, v5
	s_nop 0
	v_lshlrev_b32_e32 v4, 16, v0
	v_and_b32_e32 v5, 0xffff0000, v0
	v_pk_mul_f32 v[4:5], v[110:111], v[4:5] op_sel_hi:[0,1]
	v_cvt_pk_bf16_f32 v0, v4, v5
	v_lshlrev_b32_e32 v4, 16, v1
	v_and_b32_e32 v5, 0xffff0000, v1
	v_pk_mul_f32 v[4:5], v[110:111], v[4:5] op_sel_hi:[0,1]
	v_cvt_pk_bf16_f32 v1, v4, v5
	v_lshlrev_b32_e32 v4, 16, v2
	v_and_b32_e32 v5, 0xffff0000, v2
	v_pk_mul_f32 v[4:5], v[110:111], v[4:5] op_sel_hi:[0,1]
	v_cvt_pk_bf16_f32 v2, v4, v5
	v_lshlrev_b32_e32 v4, 16, v3
	v_and_b32_e32 v5, 0xffff0000, v3
	v_pk_mul_f32 v[4:5], v[110:111], v[4:5] op_sel_hi:[0,1]
	v_cvt_pk_bf16_f32 v3, v4, v5
	ds_read_b128 v[4:7], v157 offset:34816
	ds_read_b128 v[100:103], v157 offset:39168
	ds_read_b128 v[104:107], v157 offset:43520
	ds_read_b128 v[110:113], v157 offset:47872
	ds_read_b128 v[114:117], v157 offset:52224
	ds_read_b128 v[118:121], v157 offset:56576
	ds_read_b128 v[122:125], v157 offset:60928
	ds_read_b128 v[130:133], v157 offset:65280
	s_setprio 1
	s_waitcnt lgkmcnt(7)
	v_mfma_f32_16x16x32_bf16 v[32:35], v[4:7], v[28:31], v[32:35]
	v_mfma_f32_16x16x32_bf16 v[4:7], v[4:7], v[24:27], v[36:39]
	s_waitcnt lgkmcnt(6)
	v_mfma_f32_16x16x32_bf16 v[36:39], v[100:103], v[28:31], v[40:43]
	v_mfma_f32_16x16x32_bf16 v[40:43], v[100:103], v[24:27], v[44:47]
	s_waitcnt lgkmcnt(5)
	v_mfma_f32_16x16x32_bf16 v[44:47], v[104:107], v[28:31], v[48:51]
	v_mfma_f32_16x16x32_bf16 v[48:51], v[104:107], v[24:27], v[52:55]
	s_waitcnt lgkmcnt(4)
	v_mfma_f32_16x16x32_bf16 v[52:55], v[110:113], v[28:31], v[56:59]
	v_mfma_f32_16x16x32_bf16 v[56:59], v[110:113], v[24:27], v[60:63]
	s_waitcnt lgkmcnt(3)
	v_mfma_f32_16x16x32_bf16 v[60:63], v[114:117], v[28:31], v[64:67]
	v_mfma_f32_16x16x32_bf16 v[64:67], v[114:117], v[24:27], v[68:71]
	s_waitcnt lgkmcnt(2)
	v_mfma_f32_16x16x32_bf16 v[68:71], v[118:121], v[28:31], v[72:75]
	v_mfma_f32_16x16x32_bf16 v[72:75], v[118:121], v[24:27], v[76:79]
	s_waitcnt lgkmcnt(1)
	v_mfma_f32_16x16x32_bf16 v[76:79], v[122:125], v[28:31], v[80:83]
	v_mfma_f32_16x16x32_bf16 v[80:83], v[122:125], v[24:27], v[84:87]
	s_waitcnt lgkmcnt(0)
	v_mfma_f32_16x16x32_bf16 v[28:31], v[130:133], v[28:31], v[88:91]
	v_mfma_f32_16x16x32_bf16 v[24:27], v[130:133], v[24:27], v[92:95]
	s_setprio 0
	ds_read_b128 v[84:87], v157 offset:34880
	ds_read_b128 v[88:91], v157 offset:39232
	ds_read_b128 v[92:95], v157 offset:43584
	ds_read_b128 v[100:103], v157 offset:47936
	ds_read_b128 v[104:107], v157 offset:52288
	ds_read_b128 v[110:113], v157 offset:56640
	ds_read_b128 v[114:117], v157 offset:60992
	ds_read_b128 v[118:121], v157 offset:65344
	s_setprio 1
	s_waitcnt lgkmcnt(7)
	v_mfma_f32_16x16x32_bf16 v[32:35], v[84:87], v[20:23], v[32:35]
	v_mfma_f32_16x16x32_bf16 v[4:7], v[84:87], v[16:19], v[4:7]
	s_waitcnt lgkmcnt(6)
	v_mfma_f32_16x16x32_bf16 v[36:39], v[88:91], v[20:23], v[36:39]
	v_mfma_f32_16x16x32_bf16 v[40:43], v[88:91], v[16:19], v[40:43]
	s_waitcnt lgkmcnt(5)
	v_mfma_f32_16x16x32_bf16 v[44:47], v[92:95], v[20:23], v[44:47]
	v_mfma_f32_16x16x32_bf16 v[48:51], v[92:95], v[16:19], v[48:51]
	s_waitcnt lgkmcnt(4)
	v_mfma_f32_16x16x32_bf16 v[52:55], v[100:103], v[20:23], v[52:55]
	v_mfma_f32_16x16x32_bf16 v[56:59], v[100:103], v[16:19], v[56:59]
	s_waitcnt lgkmcnt(3)
	v_mfma_f32_16x16x32_bf16 v[60:63], v[104:107], v[20:23], v[60:63]
	v_mfma_f32_16x16x32_bf16 v[64:67], v[104:107], v[16:19], v[64:67]
	s_waitcnt lgkmcnt(2)
	v_mfma_f32_16x16x32_bf16 v[68:71], v[110:113], v[20:23], v[68:71]
	v_mfma_f32_16x16x32_bf16 v[72:75], v[110:113], v[16:19], v[72:75]
	s_waitcnt lgkmcnt(1)
	v_mfma_f32_16x16x32_bf16 v[76:79], v[114:117], v[20:23], v[76:79]
	v_mfma_f32_16x16x32_bf16 v[80:83], v[114:117], v[16:19], v[80:83]
	s_waitcnt lgkmcnt(0)
	v_mfma_f32_16x16x32_bf16 v[20:23], v[118:121], v[20:23], v[28:31]
	v_mfma_f32_16x16x32_bf16 v[16:19], v[118:121], v[16:19], v[24:27]
	s_setprio 0
	s_nop 1
	ds_read_b128 v[24:27], v157 offset:34944
	ds_read_b128 v[28:31], v157 offset:39296
	ds_read_b128 v[84:87], v157 offset:43648
	ds_read_b128 v[88:91], v157 offset:48000
	ds_read_b128 v[92:95], v157 offset:52352
	ds_read_b128 v[100:103], v157 offset:56704
	ds_read_b128 v[104:107], v157 offset:61056
	ds_read_b128 v[110:113], v157 offset:65408
	s_setprio 1
	s_waitcnt lgkmcnt(7)
	v_mfma_f32_16x16x32_bf16 v[32:35], v[24:27], v[12:15], v[32:35]
	v_mfma_f32_16x16x32_bf16 v[4:7], v[24:27], v[8:11], v[4:7]
	s_waitcnt lgkmcnt(6)
	v_mfma_f32_16x16x32_bf16 v[24:27], v[28:31], v[12:15], v[36:39]
	v_mfma_f32_16x16x32_bf16 v[36:39], v[28:31], v[8:11], v[40:43]
	s_waitcnt lgkmcnt(5)
	v_mfma_f32_16x16x32_bf16 v[40:43], v[84:87], v[12:15], v[44:47]
	v_mfma_f32_16x16x32_bf16 v[44:47], v[84:87], v[8:11], v[48:51]
	s_waitcnt lgkmcnt(4)
	v_mfma_f32_16x16x32_bf16 v[48:51], v[88:91], v[12:15], v[52:55]
	v_mfma_f32_16x16x32_bf16 v[84:87], v[88:91], v[8:11], v[56:59]
	s_waitcnt lgkmcnt(3)
	v_mfma_f32_16x16x32_bf16 v[88:91], v[92:95], v[12:15], v[60:63]
	v_mfma_f32_16x16x32_bf16 v[64:67], v[92:95], v[8:11], v[64:67]
	s_waitcnt lgkmcnt(2)
	v_mfma_f32_16x16x32_bf16 v[68:71], v[100:103], v[12:15], v[68:71]
	v_mfma_f32_16x16x32_bf16 v[72:75], v[100:103], v[8:11], v[72:75]
	s_waitcnt lgkmcnt(1)
	v_mfma_f32_16x16x32_bf16 v[76:79], v[104:107], v[12:15], v[76:79]
	v_mfma_f32_16x16x32_bf16 v[80:83], v[104:107], v[8:11], v[80:83]
	s_waitcnt lgkmcnt(0)
	v_mfma_f32_16x16x32_bf16 v[92:95], v[110:113], v[12:15], v[20:23]
	v_mfma_f32_16x16x32_bf16 v[100:103], v[110:113], v[8:11], v[16:19]
	s_setprio 0
	ds_read_b128 v[8:11], v157 offset:35008
	ds_read_b128 v[12:15], v157 offset:39360
	ds_read_b128 v[16:19], v157 offset:43712
	ds_read_b128 v[104:107], v157 offset:48064
	ds_read_b128 v[110:113], v157 offset:52416
	ds_read_b128 v[114:117], v157 offset:56768
	ds_read_b128 v[118:121], v157 offset:61120
	ds_read_b128 v[122:125], v157 offset:65472
	s_setprio 1
	s_waitcnt lgkmcnt(7)
	v_mfma_f32_16x16x32_bf16 v[60:63], v[8:11], v[96:99], v[32:35]
	v_mfma_f32_16x16x32_bf16 v[28:31], v[8:11], v[0:3], v[4:7]
	s_waitcnt lgkmcnt(6)
	v_mfma_f32_16x16x32_bf16 v[56:59], v[12:15], v[96:99], v[24:27]
	v_mfma_f32_16x16x32_bf16 v[24:27], v[12:15], v[0:3], v[36:39]
	s_waitcnt lgkmcnt(5)
	v_mfma_f32_16x16x32_bf16 v[52:55], v[16:19], v[96:99], v[40:43]
	v_mfma_f32_16x16x32_bf16 v[20:23], v[16:19], v[0:3], v[44:47]
	s_waitcnt lgkmcnt(4)
	v_mfma_f32_16x16x32_bf16 v[48:51], v[104:107], v[96:99], v[48:51]
	v_mfma_f32_16x16x32_bf16 v[16:19], v[104:107], v[0:3], v[84:87]
	s_waitcnt lgkmcnt(3)
	v_mfma_f32_16x16x32_bf16 v[44:47], v[110:113], v[96:99], v[88:91]
	v_mfma_f32_16x16x32_bf16 v[12:15], v[110:113], v[0:3], v[64:67]
	s_waitcnt lgkmcnt(2)
	v_mfma_f32_16x16x32_bf16 v[40:43], v[114:117], v[96:99], v[68:71]
	v_mfma_f32_16x16x32_bf16 v[8:11], v[114:117], v[0:3], v[72:75]
	s_waitcnt lgkmcnt(1)
	v_mfma_f32_16x16x32_bf16 v[36:39], v[118:121], v[96:99], v[76:79]
	v_mfma_f32_16x16x32_bf16 v[4:7], v[118:121], v[0:3], v[80:83]
	s_waitcnt lgkmcnt(0)
	v_mfma_f32_16x16x32_bf16 v[32:35], v[122:125], v[96:99], v[92:95]
	v_mfma_f32_16x16x32_bf16 v[0:3], v[122:125], v[0:3], v[100:103]
	s_setprio 0
	v_mov_b32_e32 v64, v60
	v_mov_b32_e32 v65, v56
	v_mov_b32_e32 v66, v61
	v_mov_b32_e32 v67, v57
	v_pk_add_f32 v[64:65], v[64:65], v[66:67]
	v_mov_b32_e32 v66, v62
	v_mov_b32_e32 v67, v58
	v_pk_add_f32 v[64:65], v[66:67], v[64:65]
	v_mov_b32_e32 v66, v63
	v_mov_b32_e32 v67, v59
	v_pk_add_f32 v[64:65], v[66:67], v[64:65]
	v_mov_b32_e32 v66, v53
	v_add_f32_e32 v64, 0, v64
	v_add_f32_e32 v68, v64, v65
	v_mov_b32_e32 v64, v52
	v_mov_b32_e32 v65, v48
	v_mov_b32_e32 v67, v49
	v_pk_add_f32 v[64:65], v[64:65], v[66:67]
	v_mov_b32_e32 v66, v54
	v_mov_b32_e32 v67, v50
	v_pk_add_f32 v[64:65], v[66:67], v[64:65]
	v_mov_b32_e32 v66, v55
	v_mov_b32_e32 v67, v51
	v_pk_add_f32 v[64:65], v[66:67], v[64:65]
	v_mov_b32_e32 v66, v45
	v_add_f32_e32 v64, v68, v64
	v_add_f32_e32 v68, v64, v65
	v_mov_b32_e32 v64, v44
	v_mov_b32_e32 v65, v40
	v_mov_b32_e32 v67, v41
	v_pk_add_f32 v[64:65], v[64:65], v[66:67]
	v_mov_b32_e32 v66, v46
	v_mov_b32_e32 v67, v42
	v_pk_add_f32 v[64:65], v[66:67], v[64:65]
	v_mov_b32_e32 v66, v47
	v_mov_b32_e32 v67, v43
	v_pk_add_f32 v[64:65], v[66:67], v[64:65]
	v_mov_b32_e32 v66, v37
	v_add_f32_e32 v64, v68, v64
	v_add_f32_e32 v68, v64, v65
	v_mov_b32_e32 v64, v36
	v_mov_b32_e32 v65, v32
	v_mov_b32_e32 v67, v33
	v_pk_add_f32 v[64:65], v[64:65], v[66:67]
	v_mov_b32_e32 v66, v38
	v_mov_b32_e32 v67, v34
	v_pk_add_f32 v[64:65], v[66:67], v[64:65]
	v_mov_b32_e32 v66, v39
	v_mov_b32_e32 v67, v35
	v_pk_add_f32 v[64:65], v[66:67], v[64:65]
	s_load_dwordx16 s[40:55], s[0:1], 0x100
	v_add_f32_e32 v64, v68, v64
	v_add_f32_e32 v64, v64, v65
	ds_bpermute_b32 v65, v109, v64
	s_lshl_b32 s2, s57, 2
	v_readlane_b32 s4, v241, 38
	s_add_u32 s30, s4, s2
	v_readlane_b32 s2, v241, 39
	s_waitcnt lgkmcnt(0)
	v_add_f32_e32 v65, v64, v65
	ds_bpermute_b32 v66, v154, v65
	v_add_u32_e32 v64, s66, v108
	s_addc_u32 s31, s2, 0
	s_lshl_b32 s96, s57, 1
	v_lshlrev_b32_e32 v128, 1, v156
	s_waitcnt lgkmcnt(0)
	v_add_f32_e32 v69, v65, v66
	v_ashrrev_i32_e32 v65, 31, v64
	v_lshlrev_b64 v[66:67], 14, v[64:65]
	v_lshl_add_u64 v[66:67], s[52:53], 0, v[66:67]
	v_lshl_add_u64 v[66:67], v[66:67], 0, s[96:97]
	v_lshl_add_u64 v[78:79], v[66:67], 0, v[128:129]
	s_movk_i32 s38, 0x1000
	v_add_co_u32_e32 v66, vcc, s38, v78
	v_lshlrev_b32_e32 v68, 2, v156
	s_nop 0
	v_addc_co_u32_e32 v67, vcc, 0, v79, vcc
	global_load_dwordx2 v[80:81], v[66:67], off offset:2048
	global_load_dwordx4 v[70:73], v68, s[30:31]
	v_fmamk_f32 v77, v69, 0xbc000000, v61
	v_fmamk_f32 v76, v69, 0xbc000000, v60
	v_mul_f32_e32 v75, v77, v77
	v_fmac_f32_e32 v75, v76, v76
	v_fmamk_f32 v62, v69, 0xbc000000, v62
	v_fmac_f32_e32 v75, v62, v62
	v_fmac_f32_e32 v63, 0xbc000000, v69
	v_fmac_f32_e32 v75, v63, v63
	v_fmamk_f32 v60, v69, 0xbc000000, v56
	v_fmac_f32_e32 v75, v60, v60
	v_fmamk_f32 v61, v69, 0xbc000000, v57
	v_fmac_f32_e32 v75, v61, v61
	v_fmamk_f32 v58, v69, 0xbc000000, v58
	v_fmac_f32_e32 v75, v58, v58
	v_fmac_f32_e32 v59, 0xbc000000, v69
	v_fmac_f32_e32 v75, v59, v59
	v_fmamk_f32 v82, v69, 0xbc000000, v52
	v_fmac_f32_e32 v75, v82, v82
	v_fmamk_f32 v83, v69, 0xbc000000, v53
	v_fmac_f32_e32 v75, v83, v83
	v_fmamk_f32 v54, v69, 0xbc000000, v54
	v_fmac_f32_e32 v75, v54, v54
	v_fmac_f32_e32 v55, 0xbc000000, v69
	v_fmac_f32_e32 v75, v55, v55
	v_fmamk_f32 v66, v69, 0xbc000000, v48
	v_fmac_f32_e32 v75, v66, v66
	v_fmamk_f32 v67, v69, 0xbc000000, v49
	v_fmac_f32_e32 v75, v67, v67
	v_fmamk_f32 v50, v69, 0xbc000000, v50
	v_fmac_f32_e32 v75, v50, v50
	v_fmac_f32_e32 v51, 0xbc000000, v69
	v_fmac_f32_e32 v75, v51, v51
	v_fmamk_f32 v56, v69, 0xbc000000, v44
	v_fmac_f32_e32 v75, v56, v56
	v_fmamk_f32 v57, v69, 0xbc000000, v45
	v_fmac_f32_e32 v75, v57, v57
	v_fmamk_f32 v46, v69, 0xbc000000, v46
	v_fmac_f32_e32 v75, v46, v46
	v_fmac_f32_e32 v47, 0xbc000000, v69
	v_fmac_f32_e32 v75, v47, v47
	v_fmamk_f32 v52, v69, 0xbc000000, v40
	v_fmac_f32_e32 v75, v52, v52
	v_fmamk_f32 v53, v69, 0xbc000000, v41
	v_fmac_f32_e32 v75, v53, v53
	v_fmamk_f32 v42, v69, 0xbc000000, v42
	v_fmac_f32_e32 v75, v42, v42
	v_fmac_f32_e32 v43, 0xbc000000, v69
	v_mul_f32_e32 v74, 0x3c000000, v69
	v_fmac_f32_e32 v75, v43, v43
	v_pk_add_f32 v[40:41], v[36:37], v[74:75] op_sel_hi:[1,0] neg_lo:[0,1] neg_hi:[0,1]
	s_mov_b32 s2, 0x800000
	v_pk_mul_f32 v[40:41], v[40:41], v[40:41]
	s_load_dwordx16 s[4:19], s[0:1], 0x140
	v_add_f32_e32 v40, v40, v75
	v_add_f32_e32 v44, v41, v40
	v_pk_add_f32 v[40:41], v[38:39], v[74:75] op_sel_hi:[1,0] neg_lo:[0,1] neg_hi:[0,1]
	s_mov_b64 s[40:41], 0x1800
	v_pk_mul_f32 v[40:41], v[40:41], v[40:41]
	v_fmamk_f32 v37, v69, 0xbc000000, v37
	v_add_f32_e32 v40, v40, v44
	v_add_f32_e32 v44, v41, v40
	v_pk_add_f32 v[40:41], v[32:33], v[74:75] op_sel_hi:[1,0] neg_lo:[0,1] neg_hi:[0,1]
	v_fmamk_f32 v36, v69, 0xbc000000, v36
	v_pk_mul_f32 v[40:41], v[40:41], v[40:41]
	v_fmamk_f32 v39, v69, 0xbc000000, v39
	v_add_f32_e32 v40, v40, v44
	v_add_f32_e32 v44, v41, v40
	v_pk_add_f32 v[40:41], v[34:35], v[74:75] op_sel_hi:[1,0] neg_lo:[0,1] neg_hi:[0,1]
	v_fmac_f32_e32 v38, 0xbc000000, v69
	v_pk_mul_f32 v[40:41], v[40:41], v[40:41]
	v_fmamk_f32 v33, v69, 0xbc000000, v33
	v_add_f32_e32 v40, v40, v44
	v_add_f32_e32 v40, v41, v40
	ds_bpermute_b32 v41, v109, v40
	v_fmamk_f32 v32, v69, 0xbc000000, v32
	v_fmamk_f32 v35, v69, 0xbc000000, v35
	v_fmac_f32_e32 v34, 0xbc000000, v69
	s_add_i32 s70, s70, s64
	s_waitcnt lgkmcnt(0)
	v_add_f32_e32 v40, v40, v41
	ds_bpermute_b32 v41, v154, v40
	s_waitcnt vmcnt(1)
	v_and_b32_e32 v45, 0xffff0000, v80
	v_lshlrev_b32_e32 v48, 16, v81
	v_and_b32_e32 v49, 0xffff0000, v81
	s_cmpk_gt_i32 s70, 0x41f
	s_waitcnt lgkmcnt(0)
	v_add_f32_e32 v40, v40, v41
	v_fmamk_f32 v40, v40, 0x3c000000, v163
	v_mul_f32_e32 v41, 0x4b800000, v40
	v_cmp_gt_f32_e32 vcc, s2, v40
	s_nop 1
	v_cndmask_b32_e32 v40, v40, v41, vcc
	v_rsq_f32_e32 v40, v40
	s_nop 0
	v_mul_f32_e32 v41, 0x45800000, v40
	v_cndmask_b32_e32 v40, v40, v41, vcc
	v_lshlrev_b32_e32 v41, 16, v80
	v_mul_f32_e32 v41, 0xbfb8aa3b, v41
	v_exp_f32_e32 v41, v41
	v_lshlrev_b64 v[80:81], 11, v[64:65]
	v_add_f32_e32 v41, 1.0, v41
	v_rcp_f32_e32 v44, v41
	v_mul_f32_e32 v41, 0xbfb8aa3b, v45
	v_mul_f32_e32 v45, 0xbfb8aa3b, v48
	v_exp_f32_e32 v45, v45
	v_mul_f32_e32 v48, 0xbfb8aa3b, v49
	v_exp_f32_e32 v41, v41
	v_exp_f32_e32 v48, v48
	v_add_f32_e32 v45, 1.0, v45
	v_rcp_f32_e32 v74, v45
	v_add_f32_e32 v41, 1.0, v41
	v_add_f32_e32 v45, 1.0, v48
	v_rcp_f32_e32 v75, v45
	v_rcp_f32_e32 v45, v41
	v_lshl_add_u64 v[48:49], v[78:79], 0, s[40:41]
	global_load_dwordx2 v[204:205], v[48:49], off offset:32
	global_load_dwordx2 v[206:207], v[48:49], off offset:64
	global_load_dwordx2 v[208:209], v[48:49], off offset:96
	global_load_dwordx2 v[210:211], v[48:49], off offset:128
	global_load_dwordx2 v[216:217], v[48:49], off offset:160
	global_load_dwordx2 v[218:219], v[48:49], off offset:192
	global_load_dwordx2 v[220:221], v[48:49], off offset:224
	v_mov_b32_e32 v78, v6
	v_pk_mul_f32 v[62:63], v[62:63], v[74:75]
	v_pk_mul_f32 v[44:45], v[76:77], v[44:45]
	v_pk_mul_f32 v[62:63], v[62:63], v[40:41] op_sel_hi:[1,0]
	v_pk_mul_f32 v[44:45], v[44:45], v[40:41] op_sel_hi:[1,0]
	s_waitcnt vmcnt(0)
	v_pk_mul_f32 v[62:63], v[72:73], v[62:63]
	v_pk_mul_f32 v[44:45], v[70:71], v[44:45]
	v_cvt_pk_bf16_f32 v71, v62, v63
	v_cvt_pk_bf16_f32 v70, v44, v45
	v_lshl_add_u64 v[44:45], s[10:11], 0, v[80:81]
	v_lshl_add_u64 v[44:45], v[44:45], 0, s[96:97]
	v_lshl_add_u64 v[44:45], v[44:45], 0, v[128:129]
	global_store_dwordx2 v[44:45], v[70:71], off
	v_mov_b32_e32 v62, v204
	v_mov_b32_e32 v63, v205
	s_nop 0
	global_load_dwordx4 v[70:73], v68, s[30:31] offset:64
	v_mov_b32_e32 v76, v5
	v_mov_b32_e32 v77, v1
	v_mov_b32_e32 v79, v2
	v_mov_b32_e32 v80, v7
	v_mov_b32_e32 v81, v3
	s_waitcnt vmcnt(1)
	v_lshlrev_b32_e32 v41, 16, v62
	v_mul_f32_e32 v41, 0xbfb8aa3b, v41
	v_exp_f32_e32 v41, v41
	v_and_b32_e32 v65, 0xffff0000, v62
	v_lshlrev_b32_e32 v74, 16, v63
	v_and_b32_e32 v63, 0xffff0000, v63
	v_add_f32_e32 v41, 1.0, v41
	v_rcp_f32_e32 v62, v41
	v_mul_f32_e32 v41, 0xbfb8aa3b, v65
	v_mul_f32_e32 v65, 0xbfb8aa3b, v74
	v_mul_f32_e32 v63, 0xbfb8aa3b, v63
	v_exp_f32_e32 v41, v41
	v_exp_f32_e32 v65, v65
	v_exp_f32_e32 v63, v63
	v_add_f32_e32 v41, 1.0, v41
	v_add_f32_e32 v65, 1.0, v65
	v_add_f32_e32 v63, 1.0, v63
	v_rcp_f32_e32 v74, v65
	v_rcp_f32_e32 v75, v63
	v_rcp_f32_e32 v63, v41
	v_pk_mul_f32 v[58:59], v[58:59], v[74:75]
	v_pk_mul_f32 v[60:61], v[60:61], v[62:63]
	v_pk_mul_f32 v[58:59], v[58:59], v[40:41] op_sel_hi:[1,0]
	v_pk_mul_f32 v[60:61], v[60:61], v[40:41] op_sel_hi:[1,0]
	s_waitcnt vmcnt(0)
	v_pk_mul_f32 v[58:59], v[72:73], v[58:59]
	v_pk_mul_f32 v[60:61], v[70:71], v[60:61]
	v_mov_b32_e32 v73, v11
	v_cvt_pk_bf16_f32 v60, v60, v61
	v_cvt_pk_bf16_f32 v61, v58, v59
	global_store_dwordx2 v[44:45], v[60:61], off offset:32
	v_mov_b32_e32 v62, v206
	v_mov_b32_e32 v63, v207
	s_nop 0
	global_load_dwordx4 v[58:61], v68, s[30:31] offset:128
	v_mov_b32_e32 v74, v4
	v_mov_b32_e32 v75, v0
	s_waitcnt vmcnt(1)
	v_lshlrev_b32_e32 v41, 16, v62
	v_and_b32_e32 v62, 0xffff0000, v62
	v_lshlrev_b32_e32 v65, 16, v63
	v_and_b32_e32 v63, 0xffff0000, v63
	v_mul_f32_e32 v41, 0xbfb8aa3b, v41
	v_mul_f32_e32 v62, 0xbfb8aa3b, v62
	v_mul_f32_e32 v65, 0xbfb8aa3b, v65
	v_mul_f32_e32 v63, 0xbfb8aa3b, v63
	v_exp_f32_e32 v41, v41
	v_exp_f32_e32 v62, v62
	v_exp_f32_e32 v65, v65
	v_exp_f32_e32 v63, v63
	v_add_f32_e32 v41, 1.0, v41
	v_add_f32_e32 v72, 1.0, v62
	v_add_f32_e32 v65, 1.0, v65
	v_add_f32_e32 v63, 1.0, v63
	v_rcp_f32_e32 v62, v41
	v_rcp_f32_e32 v70, v65
	v_rcp_f32_e32 v71, v63
	v_rcp_f32_e32 v63, v72
	v_mov_b32_e32 v72, v15
	v_pk_mul_f32 v[54:55], v[54:55], v[70:71]
	v_pk_mul_f32 v[62:63], v[82:83], v[62:63]
	v_pk_mul_f32 v[54:55], v[54:55], v[40:41] op_sel_hi:[1,0]
	v_pk_mul_f32 v[62:63], v[62:63], v[40:41] op_sel_hi:[1,0]
	s_waitcnt vmcnt(0)
	v_pk_mul_f32 v[54:55], v[60:61], v[54:55]
	v_pk_mul_f32 v[58:59], v[58:59], v[62:63]
	v_mov_b32_e32 v70, v14
	v_cvt_pk_bf16_f32 v58, v58, v59
	v_cvt_pk_bf16_f32 v59, v54, v55
	global_store_dwordx2 v[44:45], v[58:59], off offset:64
	v_mov_b32_e32 v54, v208
	v_mov_b32_e32 v55, v209
	s_nop 0
	global_load_dwordx4 v[58:61], v68, s[30:31] offset:192
	v_mov_b32_e32 v71, v10
	s_waitcnt vmcnt(1)
	v_lshlrev_b32_e32 v41, 16, v54
	v_and_b32_e32 v54, 0xffff0000, v54
	v_lshlrev_b32_e32 v62, 16, v55
	v_and_b32_e32 v55, 0xffff0000, v55
	v_mul_f32_e32 v41, 0xbfb8aa3b, v41
	v_mul_f32_e32 v54, 0xbfb8aa3b, v54
	v_mul_f32_e32 v62, 0xbfb8aa3b, v62
	v_mul_f32_e32 v55, 0xbfb8aa3b, v55
	v_exp_f32_e32 v41, v41
	v_exp_f32_e32 v54, v54
	v_exp_f32_e32 v62, v62
	v_exp_f32_e32 v55, v55
	v_add_f32_e32 v41, 1.0, v41
	v_add_f32_e32 v65, 1.0, v54
	v_add_f32_e32 v62, 1.0, v62
	v_add_f32_e32 v55, 1.0, v55
	v_rcp_f32_e32 v54, v41
	v_rcp_f32_e32 v62, v62
	v_rcp_f32_e32 v63, v55
	v_rcp_f32_e32 v55, v65
	v_pk_mul_f32 v[50:51], v[50:51], v[62:63]
	v_pk_mul_f32 v[54:55], v[66:67], v[54:55]
	v_pk_mul_f32 v[50:51], v[50:51], v[40:41] op_sel_hi:[1,0]
	v_pk_mul_f32 v[54:55], v[54:55], v[40:41] op_sel_hi:[1,0]
	s_waitcnt vmcnt(0)
	v_pk_mul_f32 v[50:51], v[60:61], v[50:51]
	v_pk_mul_f32 v[54:55], v[58:59], v[54:55]
	v_mov_b32_e32 v63, v8
	v_cvt_pk_bf16_f32 v54, v54, v55
	v_cvt_pk_bf16_f32 v55, v50, v51
	global_store_dwordx2 v[44:45], v[54:55], off offset:96
	v_mov_b32_e32 v50, v210
	v_mov_b32_e32 v51, v211
	global_load_dwordx4 v[58:61], v68, s[30:31] offset:256
	v_mov_b32_e32 v66, v13
	v_mov_b32_e32 v67, v9
	s_waitcnt vmcnt(1)
	v_lshlrev_b32_e32 v41, 16, v50
	v_and_b32_e32 v50, 0xffff0000, v50
	v_lshlrev_b32_e32 v54, 16, v51
	v_and_b32_e32 v51, 0xffff0000, v51
	v_mul_f32_e32 v41, 0xbfb8aa3b, v41
	v_mul_f32_e32 v50, 0xbfb8aa3b, v50
	v_mul_f32_e32 v54, 0xbfb8aa3b, v54
	v_mul_f32_e32 v51, 0xbfb8aa3b, v51
	v_exp_f32_e32 v41, v41
	v_exp_f32_e32 v50, v50
	v_exp_f32_e32 v54, v54
	v_exp_f32_e32 v51, v51
	v_add_f32_e32 v41, 1.0, v41
	v_add_f32_e32 v62, 1.0, v50
	v_add_f32_e32 v54, 1.0, v54
	v_add_f32_e32 v51, 1.0, v51
	v_rcp_f32_e32 v50, v41
	v_rcp_f32_e32 v54, v54
	v_rcp_f32_e32 v55, v51
	v_rcp_f32_e32 v51, v62
	v_mov_b32_e32 v62, v12
	v_pk_mul_f32 v[46:47], v[46:47], v[54:55]
	v_pk_mul_f32 v[50:51], v[56:57], v[50:51]
	v_pk_mul_f32 v[46:47], v[46:47], v[40:41] op_sel_hi:[1,0]
	v_pk_mul_f32 v[50:51], v[50:51], v[40:41] op_sel_hi:[1,0]
	s_waitcnt vmcnt(0)
	v_pk_mul_f32 v[46:47], v[60:61], v[46:47]
	v_pk_mul_f32 v[50:51], v[58:59], v[50:51]
	v_mov_b32_e32 v59, v18
	v_cvt_pk_bf16_f32 v50, v50, v51
	v_cvt_pk_bf16_f32 v51, v46, v47
	global_store_dwordx2 v[44:45], v[50:51], off offset:128
	v_mov_b32_e32 v46, v216
	v_mov_b32_e32 v47, v217
	global_load_dwordx4 v[54:57], v68, s[30:31] offset:320
	v_mov_b32_e32 v60, v23
	v_mov_b32_e32 v61, v19
	s_waitcnt vmcnt(1)
	v_lshlrev_b32_e32 v41, 16, v46
	v_and_b32_e32 v46, 0xffff0000, v46
	v_lshlrev_b32_e32 v50, 16, v47
	v_and_b32_e32 v47, 0xffff0000, v47
	v_mul_f32_e32 v41, 0xbfb8aa3b, v41
	v_mul_f32_e32 v46, 0xbfb8aa3b, v46
	v_mul_f32_e32 v50, 0xbfb8aa3b, v50
	v_mul_f32_e32 v47, 0xbfb8aa3b, v47
	v_exp_f32_e32 v41, v41
	v_exp_f32_e32 v46, v46
	v_exp_f32_e32 v50, v50
	v_exp_f32_e32 v47, v47
	v_add_f32_e32 v41, 1.0, v41
	v_add_f32_e32 v58, 1.0, v46
	v_add_f32_e32 v50, 1.0, v50
	v_add_f32_e32 v47, 1.0, v47
	v_rcp_f32_e32 v46, v41
	v_rcp_f32_e32 v50, v50
	v_rcp_f32_e32 v51, v47
	v_rcp_f32_e32 v47, v58
	v_mov_b32_e32 v58, v22
	v_pk_mul_f32 v[42:43], v[42:43], v[50:51]
	v_pk_mul_f32 v[46:47], v[52:53], v[46:47]
	v_pk_mul_f32 v[42:43], v[40:41], v[42:43] op_sel_hi:[0,1]
	v_pk_mul_f32 v[46:47], v[40:41], v[46:47] op_sel_hi:[0,1]
	s_waitcnt vmcnt(0)
	v_pk_mul_f32 v[42:43], v[56:57], v[42:43]
	v_pk_mul_f32 v[46:47], v[54:55], v[46:47]
	v_mov_b32_e32 v55, v16
	v_cvt_pk_bf16_f32 v46, v46, v47
	v_cvt_pk_bf16_f32 v47, v42, v43
	global_store_dwordx2 v[44:45], v[46:47], off offset:160
	v_mov_b32_e32 v42, v218
	v_mov_b32_e32 v43, v219
	global_load_dwordx4 v[50:53], v68, s[30:31] offset:384
	v_mov_b32_e32 v56, v21
	v_mov_b32_e32 v57, v17
	s_waitcnt vmcnt(1)
	v_lshlrev_b32_e32 v41, 16, v42
	v_and_b32_e32 v42, 0xffff0000, v42
	v_lshlrev_b32_e32 v46, 16, v43
	v_and_b32_e32 v43, 0xffff0000, v43
	v_mul_f32_e32 v41, 0xbfb8aa3b, v41
	v_mul_f32_e32 v42, 0xbfb8aa3b, v42
	v_mul_f32_e32 v46, 0xbfb8aa3b, v46
	v_mul_f32_e32 v43, 0xbfb8aa3b, v43
	v_exp_f32_e32 v41, v41
	v_exp_f32_e32 v42, v42
	v_exp_f32_e32 v46, v46
	v_exp_f32_e32 v43, v43
	v_add_f32_e32 v41, 1.0, v41
	v_add_f32_e32 v54, 1.0, v42
	v_add_f32_e32 v46, 1.0, v46
	v_add_f32_e32 v43, 1.0, v43
	v_rcp_f32_e32 v42, v41
	v_rcp_f32_e32 v46, v46
	v_rcp_f32_e32 v47, v43
	v_rcp_f32_e32 v43, v54
	v_mov_b32_e32 v54, v20
	v_pk_mul_f32 v[38:39], v[38:39], v[46:47]
	v_pk_mul_f32 v[36:37], v[36:37], v[42:43]
	v_pk_mul_f32 v[38:39], v[40:41], v[38:39] op_sel_hi:[0,1]
	v_pk_mul_f32 v[36:37], v[40:41], v[36:37] op_sel_hi:[0,1]
	s_waitcnt vmcnt(0)
	v_pk_mul_f32 v[38:39], v[52:53], v[38:39]
	v_pk_mul_f32 v[36:37], v[50:51], v[36:37]
	v_mov_b32_e32 v42, v29
	v_cvt_pk_bf16_f32 v36, v36, v37
	v_cvt_pk_bf16_f32 v37, v38, v39
	global_store_dwordx2 v[44:45], v[36:37], off offset:192
	v_mov_b32_e32 v36, v220
	v_mov_b32_e32 v37, v221
	v_mov_b32_e32 v38, v28
	global_load_dwordx4 v[46:49], v68, s[30:31] offset:448
	v_mov_b32_e32 v39, v24
	v_mov_b32_e32 v43, v25
	v_mov_b32_e32 v50, v30
	v_mov_b32_e32 v51, v26
	v_pk_add_f32 v[38:39], v[38:39], v[42:43]
	v_mov_b32_e32 v52, v31
	v_mov_b32_e32 v53, v27
	v_pk_add_f32 v[38:39], v[50:51], v[38:39]
	v_pk_add_f32 v[42:43], v[54:55], v[56:57]
	v_pk_add_f32 v[38:39], v[52:53], v[38:39]
	v_pk_add_f32 v[42:43], v[58:59], v[42:43]
	v_add_f32_e32 v38, 0, v38
	v_pk_add_f32 v[54:55], v[62:63], v[66:67]
	v_pk_add_f32 v[42:43], v[60:61], v[42:43]
	v_add_f32_e32 v38, v38, v39
	v_pk_add_f32 v[50:51], v[70:71], v[54:55]
	v_add_f32_e32 v38, v38, v42
	v_pk_add_f32 v[56:57], v[74:75], v[76:77]
	v_pk_add_f32 v[50:51], v[72:73], v[50:51]
	v_add_f32_e32 v38, v38, v43
	v_pk_add_f32 v[54:55], v[78:79], v[56:57]
	v_add_f32_e32 v38, v38, v50
	v_pk_add_f32 v[52:53], v[80:81], v[54:55]
	v_add_f32_e32 v38, v38, v51
	v_add_f32_e32 v38, v38, v52
	v_add_f32_e32 v41, v38, v53
	v_add_u32_e32 v62, 16, v64
	ds_bpermute_b32 v50, v109, v41
	v_ashrrev_i32_e32 v63, 31, v62
	v_lshlrev_b64 v[38:39], 14, v[62:63]
	v_lshl_add_u64 v[38:39], s[52:53], 0, v[38:39]
	v_lshl_add_u64 v[38:39], v[38:39], 0, s[96:97]
	v_lshl_add_u64 v[42:43], v[38:39], 0, v[128:129]
	s_waitcnt lgkmcnt(0)
	v_add_f32_e32 v38, v41, v50
	ds_bpermute_b32 v39, v154, v38
	v_add_co_u32_e32 v50, vcc, s38, v42
	s_waitcnt lgkmcnt(0)
	v_add_f32_e32 v38, v38, v39
	v_fmamk_f32 v54, v38, 0xbc000000, v28
	v_fmamk_f32 v55, v38, 0xbc000000, v29
	v_addc_co_u32_e32 v51, vcc, 0, v43, vcc
	v_mul_f32_e32 v39, v55, v55
	v_fmamk_f32 v30, v38, 0xbc000000, v30
	v_fmac_f32_e32 v39, v54, v54
	v_fmac_f32_e32 v31, 0xbc000000, v38
	v_fmac_f32_e32 v39, v30, v30
	v_fmac_f32_e32 v39, v31, v31
	v_fmamk_f32 v26, v38, 0xbc000000, v26
	v_fmac_f32_e32 v27, 0xbc000000, v38
	v_fmamk_f32 v22, v38, 0xbc000000, v22
	v_fmac_f32_e32 v23, 0xbc000000, v38
	v_fmamk_f32 v18, v38, 0xbc000000, v18
	v_fmac_f32_e32 v19, 0xbc000000, v38
	v_fmamk_f32 v14, v38, 0xbc000000, v14
	v_fmac_f32_e32 v15, 0xbc000000, v38
	v_mul_f32_e32 v52, 0x3c000000, v38
	v_fmamk_f32 v10, v38, 0xbc000000, v10
	v_fmac_f32_e32 v11, 0xbc000000, v38
	s_waitcnt vmcnt(1)
	v_lshlrev_b32_e32 v28, 16, v36
	v_and_b32_e32 v29, 0xffff0000, v36
	v_lshlrev_b32_e32 v36, 16, v37
	v_and_b32_e32 v37, 0xffff0000, v37
	v_mul_f32_e32 v28, 0xbfb8aa3b, v28
	v_mul_f32_e32 v29, 0xbfb8aa3b, v29
	v_mul_f32_e32 v36, 0xbfb8aa3b, v36
	v_mul_f32_e32 v37, 0xbfb8aa3b, v37
	v_exp_f32_e32 v28, v28
	v_exp_f32_e32 v29, v29
	v_exp_f32_e32 v36, v36
	v_exp_f32_e32 v37, v37
	v_add_f32_e32 v28, 1.0, v28
	v_add_f32_e32 v29, 1.0, v29
	v_add_f32_e32 v36, 1.0, v36
	v_add_f32_e32 v37, 1.0, v37
	v_rcp_f32_e32 v28, v28
	v_rcp_f32_e32 v36, v36
	v_rcp_f32_e32 v37, v37
	v_rcp_f32_e32 v29, v29
	v_pk_mul_f32 v[34:35], v[34:35], v[36:37]
	v_pk_mul_f32 v[28:29], v[32:33], v[28:29]
	v_pk_mul_f32 v[32:33], v[40:41], v[34:35] op_sel_hi:[0,1]
	v_pk_mul_f32 v[28:29], v[40:41], v[28:29] op_sel_hi:[0,1]
	s_waitcnt vmcnt(0)
	v_pk_mul_f32 v[32:33], v[48:49], v[32:33]
	v_pk_mul_f32 v[28:29], v[46:47], v[28:29]
	v_pk_add_f32 v[46:47], v[2:3], v[52:53] op_sel_hi:[1,0] neg_lo:[0,1] neg_hi:[0,1]
	v_cvt_pk_bf16_f32 v28, v28, v29
	v_cvt_pk_bf16_f32 v29, v32, v33
	global_store_dwordx2 v[44:45], v[28:29], off offset:224
	global_load_dwordx2 v[40:41], v[50:51], off offset:2048
	global_load_dwordx4 v[34:37], v68, s[30:31]
	v_fmamk_f32 v44, v38, 0xbc000000, v24
	v_fmamk_f32 v45, v38, 0xbc000000, v25
	v_fmac_f32_e32 v39, v44, v44
	v_fmac_f32_e32 v39, v45, v45
	v_fmac_f32_e32 v39, v26, v26
	v_fmamk_f32 v32, v38, 0xbc000000, v20
	v_fmac_f32_e32 v39, v27, v27
	v_fmamk_f32 v33, v38, 0xbc000000, v21
	v_fmac_f32_e32 v39, v32, v32
	v_fmac_f32_e32 v39, v33, v33
	v_fmac_f32_e32 v39, v22, v22
	v_fmamk_f32 v28, v38, 0xbc000000, v16
	v_fmac_f32_e32 v39, v23, v23
	v_fmamk_f32 v29, v38, 0xbc000000, v17
	v_fmac_f32_e32 v39, v28, v28
	v_fmac_f32_e32 v39, v29, v29
	v_fmac_f32_e32 v39, v18, v18
	v_fmamk_f32 v24, v38, 0xbc000000, v12
	v_fmac_f32_e32 v39, v19, v19
	v_fmamk_f32 v25, v38, 0xbc000000, v13
	v_fmac_f32_e32 v39, v24, v24
	v_fmac_f32_e32 v39, v25, v25
	v_fmac_f32_e32 v39, v14, v14
	v_fmamk_f32 v16, v38, 0xbc000000, v8
	v_fmac_f32_e32 v39, v15, v15
	v_fmamk_f32 v17, v38, 0xbc000000, v9
	v_fmac_f32_e32 v39, v16, v16
	v_fmac_f32_e32 v39, v17, v17
	v_pk_add_f32 v[8:9], v[4:5], v[52:53] op_sel_hi:[1,0] neg_lo:[0,1] neg_hi:[0,1]
	v_fmac_f32_e32 v39, v10, v10
	v_pk_mul_f32 v[8:9], v[8:9], v[8:9]
	v_fmac_f32_e32 v39, v11, v11
	v_pk_add_f32 v[12:13], v[6:7], v[52:53] op_sel_hi:[1,0] neg_lo:[0,1] neg_hi:[0,1]
	v_add_f32_e32 v8, v8, v39
	v_pk_mul_f32 v[12:13], v[12:13], v[12:13]
	v_add_f32_e32 v8, v9, v8
	v_pk_add_f32 v[20:21], v[0:1], v[52:53] op_sel_hi:[1,0] neg_lo:[0,1] neg_hi:[0,1]
	v_add_f32_e32 v8, v12, v8
	v_pk_mul_f32 v[20:21], v[20:21], v[20:21]
	v_add_f32_e32 v8, v13, v8
	v_add_f32_e32 v8, v20, v8
	v_pk_mul_f32 v[46:47], v[46:47], v[46:47]
	v_add_f32_e32 v8, v21, v8
	v_add_f32_e32 v8, v46, v8
	v_add_f32_e32 v12, v47, v8
	ds_bpermute_b32 v13, v109, v12
	v_lshl_add_u64 v[20:21], v[42:43], 0, s[40:41]
	global_load_dwordx2 v[222:223], v[20:21], off offset:32
	global_load_dwordx2 v[224:225], v[20:21], off offset:64
	global_load_dwordx2 v[226:227], v[20:21], off offset:96
	global_load_dwordx2 v[228:229], v[20:21], off offset:128
	global_load_dwordx2 v[230:231], v[20:21], off offset:160
	global_load_dwordx2 v[232:233], v[20:21], off offset:192
	global_load_dwordx2 v[234:235], v[20:21], off offset:224
	v_lshlrev_b64 v[8:9], 11, v[62:63]
	v_lshl_add_u64 v[8:9], s[10:11], 0, v[8:9]
	v_lshl_add_u64 v[8:9], v[8:9], 0, s[96:97]
	s_waitcnt lgkmcnt(0)
	v_add_f32_e32 v12, v12, v13
	ds_bpermute_b32 v13, v154, v12
	v_lshl_add_u64 v[8:9], v[8:9], 0, v[128:129]
	v_fmamk_f32 v5, v38, 0xbc000000, v5
	v_fmamk_f32 v4, v38, 0xbc000000, v4
	v_fmamk_f32 v7, v38, 0xbc000000, v7
	s_waitcnt lgkmcnt(0)
	v_add_f32_e32 v12, v12, v13
	v_fmamk_f32 v12, v12, 0x3c000000, v163
	v_mul_f32_e32 v13, 0x4b800000, v12
	v_cmp_gt_f32_e32 vcc, s2, v12
	v_fmac_f32_e32 v6, 0xbc000000, v38
	v_fmamk_f32 v1, v38, 0xbc000000, v1
	v_cndmask_b32_e32 v12, v12, v13, vcc
	v_rsq_f32_e32 v12, v12
	v_fmamk_f32 v0, v38, 0xbc000000, v0
	v_fmamk_f32 v3, v38, 0xbc000000, v3
	v_fmac_f32_e32 v2, 0xbc000000, v38
	s_waitcnt vmcnt(1)
	v_lshlrev_b32_e32 v13, 16, v40
	v_and_b32_e32 v39, 0xffff0000, v40
	v_lshlrev_b32_e32 v40, 16, v41
	v_and_b32_e32 v41, 0xffff0000, v41
	v_mul_f32_e32 v13, 0xbfb8aa3b, v13
	v_mul_f32_e32 v39, 0xbfb8aa3b, v39
	v_mul_f32_e32 v40, 0xbfb8aa3b, v40
	v_mul_f32_e32 v41, 0xbfb8aa3b, v41
	v_exp_f32_e32 v13, v13
	v_exp_f32_e32 v39, v39
	v_exp_f32_e32 v40, v40
	v_exp_f32_e32 v41, v41
	v_add_f32_e32 v13, 1.0, v13
	v_add_f32_e32 v39, 1.0, v39
	v_add_f32_e32 v42, 1.0, v40
	v_add_f32_e32 v41, 1.0, v41
	v_rcp_f32_e32 v40, v13
	v_rcp_f32_e32 v42, v42
	v_rcp_f32_e32 v43, v41
	v_rcp_f32_e32 v41, v39
	v_mul_f32_e32 v13, 0x45800000, v12
	v_cndmask_b32_e32 v12, v12, v13, vcc
	v_pk_mul_f32 v[30:31], v[30:31], v[42:43]
	v_pk_mul_f32 v[40:41], v[54:55], v[40:41]
	v_pk_mul_f32 v[30:31], v[30:31], v[12:13] op_sel_hi:[1,0]
	v_pk_mul_f32 v[40:41], v[40:41], v[12:13] op_sel_hi:[1,0]
	s_waitcnt vmcnt(0)
	v_pk_mul_f32 v[30:31], v[36:37], v[30:31]
	v_pk_mul_f32 v[34:35], v[34:35], v[40:41]
	s_nop 0
	v_cvt_pk_bf16_f32 v34, v34, v35
	v_cvt_pk_bf16_f32 v35, v30, v31
	global_store_dwordx2 v[8:9], v[34:35], off
	v_mov_b32_e32 v30, v222
	v_mov_b32_e32 v31, v223
	s_nop 0
	global_load_dwordx4 v[34:37], v68, s[30:31] offset:64
	s_waitcnt vmcnt(1)
	v_lshlrev_b32_e32 v13, 16, v30
	v_and_b32_e32 v30, 0xffff0000, v30
	v_lshlrev_b32_e32 v39, 16, v31
	v_and_b32_e32 v31, 0xffff0000, v31
	v_mul_f32_e32 v13, 0xbfb8aa3b, v13
	v_mul_f32_e32 v30, 0xbfb8aa3b, v30
	v_mul_f32_e32 v39, 0xbfb8aa3b, v39
	v_mul_f32_e32 v31, 0xbfb8aa3b, v31
	v_exp_f32_e32 v13, v13
	v_exp_f32_e32 v30, v30
	v_exp_f32_e32 v39, v39
	v_exp_f32_e32 v31, v31
	v_add_f32_e32 v13, 1.0, v13
	v_add_f32_e32 v42, 1.0, v30
	v_add_f32_e32 v39, 1.0, v39
	v_add_f32_e32 v31, 1.0, v31
	v_rcp_f32_e32 v30, v13
	v_rcp_f32_e32 v40, v39
	v_rcp_f32_e32 v41, v31
	v_rcp_f32_e32 v31, v42
	v_pk_mul_f32 v[26:27], v[26:27], v[40:41]
	v_pk_mul_f32 v[30:31], v[44:45], v[30:31]
	v_pk_mul_f32 v[26:27], v[26:27], v[12:13] op_sel_hi:[1,0]
	v_pk_mul_f32 v[30:31], v[30:31], v[12:13] op_sel_hi:[1,0]
	s_waitcnt vmcnt(0)
	v_pk_mul_f32 v[26:27], v[36:37], v[26:27]
	v_pk_mul_f32 v[30:31], v[34:35], v[30:31]
	s_nop 0
	v_cvt_pk_bf16_f32 v30, v30, v31
	v_cvt_pk_bf16_f32 v31, v26, v27
	global_store_dwordx2 v[8:9], v[30:31], off offset:32
	v_mov_b32_e32 v26, v224
	v_mov_b32_e32 v27, v225
	global_load_dwordx4 v[34:37], v68, s[30:31] offset:128
	s_waitcnt vmcnt(1)
	v_lshlrev_b32_e32 v13, 16, v26
	v_and_b32_e32 v26, 0xffff0000, v26
	v_lshlrev_b32_e32 v30, 16, v27
	v_and_b32_e32 v27, 0xffff0000, v27
	v_mul_f32_e32 v13, 0xbfb8aa3b, v13
	v_mul_f32_e32 v26, 0xbfb8aa3b, v26
	v_mul_f32_e32 v30, 0xbfb8aa3b, v30
	v_mul_f32_e32 v27, 0xbfb8aa3b, v27
	v_exp_f32_e32 v13, v13
	v_exp_f32_e32 v26, v26
	v_exp_f32_e32 v30, v30
	v_exp_f32_e32 v27, v27
	v_add_f32_e32 v13, 1.0, v13
	v_add_f32_e32 v39, 1.0, v26
	v_add_f32_e32 v30, 1.0, v30
	v_add_f32_e32 v27, 1.0, v27
	v_rcp_f32_e32 v26, v13
	v_rcp_f32_e32 v30, v30
	v_rcp_f32_e32 v31, v27
	v_rcp_f32_e32 v27, v39
	v_pk_mul_f32 v[22:23], v[22:23], v[30:31]
	v_pk_mul_f32 v[26:27], v[32:33], v[26:27]
	v_pk_mul_f32 v[22:23], v[22:23], v[12:13] op_sel_hi:[1,0]
	v_pk_mul_f32 v[26:27], v[26:27], v[12:13] op_sel_hi:[1,0]
	s_waitcnt vmcnt(0)
	v_pk_mul_f32 v[22:23], v[36:37], v[22:23]
	v_pk_mul_f32 v[26:27], v[34:35], v[26:27]
	s_nop 0
	v_cvt_pk_bf16_f32 v26, v26, v27
	v_cvt_pk_bf16_f32 v27, v22, v23
	global_store_dwordx2 v[8:9], v[26:27], off offset:64
	v_mov_b32_e32 v22, v226
	v_mov_b32_e32 v23, v227
	global_load_dwordx4 v[30:33], v68, s[30:31] offset:192
	s_waitcnt vmcnt(1)
	v_lshlrev_b32_e32 v13, 16, v22
	v_and_b32_e32 v22, 0xffff0000, v22
	v_lshlrev_b32_e32 v26, 16, v23
	v_and_b32_e32 v23, 0xffff0000, v23
	v_mul_f32_e32 v13, 0xbfb8aa3b, v13
	v_mul_f32_e32 v22, 0xbfb8aa3b, v22
	v_mul_f32_e32 v26, 0xbfb8aa3b, v26
	v_mul_f32_e32 v23, 0xbfb8aa3b, v23
	v_exp_f32_e32 v13, v13
	v_exp_f32_e32 v22, v22
	v_exp_f32_e32 v26, v26
	v_exp_f32_e32 v23, v23
	v_add_f32_e32 v13, 1.0, v13
	v_add_f32_e32 v34, 1.0, v22
	v_add_f32_e32 v26, 1.0, v26
	v_add_f32_e32 v23, 1.0, v23
	v_rcp_f32_e32 v22, v13
	v_rcp_f32_e32 v26, v26
	v_rcp_f32_e32 v27, v23
	v_rcp_f32_e32 v23, v34
	v_pk_mul_f32 v[18:19], v[18:19], v[26:27]
	v_pk_mul_f32 v[22:23], v[28:29], v[22:23]
	v_pk_mul_f32 v[18:19], v[18:19], v[12:13] op_sel_hi:[1,0]
	v_pk_mul_f32 v[22:23], v[22:23], v[12:13] op_sel_hi:[1,0]
	s_waitcnt vmcnt(0)
	v_pk_mul_f32 v[18:19], v[32:33], v[18:19]
	v_pk_mul_f32 v[22:23], v[30:31], v[22:23]
	s_nop 0
	v_cvt_pk_bf16_f32 v22, v22, v23
	v_cvt_pk_bf16_f32 v23, v18, v19
	global_store_dwordx2 v[8:9], v[22:23], off offset:96
	v_mov_b32_e32 v18, v228
	v_mov_b32_e32 v19, v229
	global_load_dwordx4 v[26:29], v68, s[30:31] offset:256
	s_waitcnt vmcnt(1)
	v_lshlrev_b32_e32 v13, 16, v18
	v_and_b32_e32 v18, 0xffff0000, v18
	v_lshlrev_b32_e32 v22, 16, v19
	v_and_b32_e32 v19, 0xffff0000, v19
	v_mul_f32_e32 v13, 0xbfb8aa3b, v13
	v_mul_f32_e32 v18, 0xbfb8aa3b, v18
	v_mul_f32_e32 v22, 0xbfb8aa3b, v22
	v_mul_f32_e32 v19, 0xbfb8aa3b, v19
	v_exp_f32_e32 v13, v13
	v_exp_f32_e32 v18, v18
	v_exp_f32_e32 v22, v22
	v_exp_f32_e32 v19, v19
	v_add_f32_e32 v13, 1.0, v13
	v_add_f32_e32 v30, 1.0, v18
	v_add_f32_e32 v22, 1.0, v22
	v_add_f32_e32 v19, 1.0, v19
	v_rcp_f32_e32 v18, v13
	v_rcp_f32_e32 v22, v22
	v_rcp_f32_e32 v23, v19
	v_rcp_f32_e32 v19, v30
	v_pk_mul_f32 v[14:15], v[14:15], v[22:23]
	v_pk_mul_f32 v[18:19], v[24:25], v[18:19]
	v_pk_mul_f32 v[14:15], v[14:15], v[12:13] op_sel_hi:[1,0]
	v_pk_mul_f32 v[18:19], v[18:19], v[12:13] op_sel_hi:[1,0]
	s_waitcnt vmcnt(0)
	v_pk_mul_f32 v[14:15], v[28:29], v[14:15]
	v_pk_mul_f32 v[18:19], v[26:27], v[18:19]
	s_nop 0
	v_cvt_pk_bf16_f32 v18, v18, v19
	v_cvt_pk_bf16_f32 v19, v14, v15
	global_store_dwordx2 v[8:9], v[18:19], off offset:128
	v_mov_b32_e32 v14, v230
	v_mov_b32_e32 v15, v231
	global_load_dwordx4 v[22:25], v68, s[30:31] offset:320
	s_waitcnt vmcnt(1)
	v_lshlrev_b32_e32 v13, 16, v14
	v_and_b32_e32 v14, 0xffff0000, v14
	v_lshlrev_b32_e32 v18, 16, v15
	v_and_b32_e32 v15, 0xffff0000, v15
	v_mul_f32_e32 v13, 0xbfb8aa3b, v13
	v_mul_f32_e32 v14, 0xbfb8aa3b, v14
	v_mul_f32_e32 v18, 0xbfb8aa3b, v18
	v_mul_f32_e32 v15, 0xbfb8aa3b, v15
	v_exp_f32_e32 v13, v13
	v_exp_f32_e32 v14, v14
	v_exp_f32_e32 v18, v18
	v_exp_f32_e32 v15, v15
	v_add_f32_e32 v13, 1.0, v13
	v_add_f32_e32 v26, 1.0, v14
	v_add_f32_e32 v18, 1.0, v18
	v_add_f32_e32 v15, 1.0, v15
	v_rcp_f32_e32 v14, v13
	v_rcp_f32_e32 v18, v18
	v_rcp_f32_e32 v19, v15
	v_rcp_f32_e32 v15, v26
	v_pk_mul_f32 v[10:11], v[10:11], v[18:19]
	v_pk_mul_f32 v[14:15], v[16:17], v[14:15]
	v_pk_mul_f32 v[10:11], v[12:13], v[10:11] op_sel_hi:[0,1]
	v_pk_mul_f32 v[14:15], v[12:13], v[14:15] op_sel_hi:[0,1]
	s_waitcnt vmcnt(0)
	v_pk_mul_f32 v[10:11], v[24:25], v[10:11]
	v_pk_mul_f32 v[14:15], v[22:23], v[14:15]
	s_nop 0
	v_cvt_pk_bf16_f32 v14, v14, v15
	v_cvt_pk_bf16_f32 v15, v10, v11
	global_store_dwordx2 v[8:9], v[14:15], off offset:160
	v_mov_b32_e32 v10, v232
	v_mov_b32_e32 v11, v233
	s_nop 0
	global_load_dwordx4 v[14:17], v68, s[30:31] offset:384
	s_waitcnt vmcnt(1)
	v_lshlrev_b32_e32 v13, 16, v10
	v_and_b32_e32 v10, 0xffff0000, v10
	v_lshlrev_b32_e32 v18, 16, v11
	v_and_b32_e32 v11, 0xffff0000, v11
	v_mul_f32_e32 v13, 0xbfb8aa3b, v13
	v_mul_f32_e32 v10, 0xbfb8aa3b, v10
	v_mul_f32_e32 v18, 0xbfb8aa3b, v18
	v_mul_f32_e32 v11, 0xbfb8aa3b, v11
	v_exp_f32_e32 v13, v13
	v_exp_f32_e32 v10, v10
	v_exp_f32_e32 v18, v18
	v_exp_f32_e32 v11, v11
	v_add_f32_e32 v13, 1.0, v13
	v_add_f32_e32 v22, 1.0, v10
	v_add_f32_e32 v18, 1.0, v18
	v_add_f32_e32 v11, 1.0, v11
	v_rcp_f32_e32 v10, v13
	v_rcp_f32_e32 v18, v18
	v_rcp_f32_e32 v19, v11
	v_rcp_f32_e32 v11, v22
	v_pk_mul_f32 v[6:7], v[6:7], v[18:19]
	v_pk_mul_f32 v[4:5], v[4:5], v[10:11]
	v_pk_mul_f32 v[6:7], v[12:13], v[6:7] op_sel_hi:[0,1]
	v_pk_mul_f32 v[4:5], v[12:13], v[4:5] op_sel_hi:[0,1]
	s_waitcnt vmcnt(0)
	v_pk_mul_f32 v[6:7], v[16:17], v[6:7]
	v_pk_mul_f32 v[4:5], v[14:15], v[4:5]
	s_nop 0
	v_cvt_pk_bf16_f32 v4, v4, v5
	v_cvt_pk_bf16_f32 v5, v6, v7
	global_store_dwordx2 v[8:9], v[4:5], off offset:192
	v_mov_b32_e32 v10, v234
	v_mov_b32_e32 v11, v235
	s_nop 0
	global_load_dwordx4 v[4:7], v68, s[30:31] offset:448
	s_waitcnt vmcnt(1)
	v_lshlrev_b32_e32 v13, 16, v10
	v_and_b32_e32 v10, 0xffff0000, v10
	v_lshlrev_b32_e32 v14, 16, v11
	v_and_b32_e32 v11, 0xffff0000, v11
	v_mul_f32_e32 v13, 0xbfb8aa3b, v13
	v_mul_f32_e32 v10, 0xbfb8aa3b, v10
	v_mul_f32_e32 v14, 0xbfb8aa3b, v14
	v_mul_f32_e32 v11, 0xbfb8aa3b, v11
	v_exp_f32_e32 v13, v13
	v_exp_f32_e32 v10, v10
	v_exp_f32_e32 v14, v14
	v_exp_f32_e32 v11, v11
	v_add_f32_e32 v13, 1.0, v13
	v_add_f32_e32 v16, 1.0, v10
	v_add_f32_e32 v14, 1.0, v14
	v_add_f32_e32 v11, 1.0, v11
	v_rcp_f32_e32 v10, v13
	v_rcp_f32_e32 v14, v14
	v_rcp_f32_e32 v15, v11
	v_rcp_f32_e32 v11, v16
	v_pk_mul_f32 v[2:3], v[2:3], v[14:15]
	v_pk_mul_f32 v[0:1], v[0:1], v[10:11]
	v_pk_mul_f32 v[2:3], v[12:13], v[2:3] op_sel_hi:[0,1]
	v_pk_mul_f32 v[0:1], v[12:13], v[0:1] op_sel_hi:[0,1]
	s_waitcnt vmcnt(0)
	v_pk_mul_f32 v[2:3], v[6:7], v[2:3]
	v_pk_mul_f32 v[0:1], v[4:5], v[0:1]
	s_nop 0
	v_cvt_pk_bf16_f32 v0, v0, v1
	v_cvt_pk_bf16_f32 v1, v2, v3
	global_store_dwordx2 v[8:9], v[0:1], off offset:224
	s_cbranch_scc1 .LBB1_806
